# GEMM units: first K-iteration peeled, its first MFMA per accumulator takes C=0; the 128 accumulator-zeroing v_mov per unit removed
# speedup vs baseline: 1.0160x; 1.0083x over previous
; #define PG8_STAGE(bufoff, gbase, voff) do { _Pragma("unroll") for (int _i = 0; _i < 2; ++_i) \
;         __builtin_amdgcn_global_load_lds((const unsigned*)((const char*)(gbase) + (voff)[_i]), (LAS unsigned*)(lds + (bufoff) + ldsw + _i * 8192), 16, 0, 0); } while (0)
; #define PG8_LDA(dst, b, h) do { _Pragma("unroll") for (int m = 0; m < 4; ++m) _Pragma("unroll") for (int k = 0; k < 2; ++k) dst[m][k] = *(const LAS bf16x8*)(lds + PG8_SA(b, h) + aoff + m * 2048 + k * 1024); } while (0)
; #define PG8_LDB(dst, b, h) do { _Pragma("unroll") for (int n = 0; n < 2; ++n) _Pragma("unroll") for (int k = 0; k < 2; ++k) dst[n][k] = *(const LAS bf16x8*)(lds + PG8_SB(b, h) + boff + n * 2048 + k * 1024); } while (0)
; #define PG8_MMA(ai, bj, At, Bt) do { __builtin_amdgcn_s_setprio(1); _Pragma("unroll") for (int m = 0; m < 4; ++m) _Pragma("unroll") for (int n = 0; n < 2; ++n) _Pragma("unroll") for (int k = 0; k < 2; ++k) \
;         acc[ai][bj][m][n] = __builtin_amdgcn_mfma_f32_16x16x32_bf16(Bt[n][k], At[m][k], acc[ai][bj][m][n], 0, 0, 0); __builtin_amdgcn_s_setprio(0); } while (0)
; #define PG8_BAR __builtin_amdgcn_s_barrier()
; template <class Epi>
; __device__ __forceinline__ void gemm_phase(LAS unsigned char* lds, const Gemm g, const StaticOrder& S, const Epi& E) {
;     ...
;         const char* nA = has_next ? (const char*)g.A + (size_t)nxt.pm * tstepA + (size_t)nxt.kt0 * kstep : cA; const char* nB = has_next ? (const char*)g.Bt + (size_t)nxt.pn * tstepB + (size_t)nxt.kt0 * kstep : cB;
;         const int nt = cur.nkt;
;         for (int t = 0; t < nt; t += 2) {
;             const bool last = (t == nt - 2);
;             const char* a1 = cA + (size_t)(t + 1) * kstep;
;             const char* a2 = last ? nA : cA + (size_t)(t + 2) * kstep; const char* b2 = last ? nB : cB + (size_t)(t + 2) * kstep;
;             const char* a3 = a2 + kstep; const char* b3 = b2 + kstep;
;             PG8_LDB(B0, 0, 0); PG8_SCHED; PG8_LDA(At, 0, 0); PG8_STAGE(PG8_SA(1, 1), a1 + hstepA, voffA);
;             PG8_WAIT_L(8); PG8_BAR; PG8_WAIT_L(0); PG8_MMA(0, 0, At, B0); PG8_BAR; PG8_SCHED;
;             PG8_LDB(B1, 0, 1); PG8_STAGE(PG8_SB(0, 0), b2, voffB);
;             PG8_BAR; PG8_WAIT_L(0); PG8_MMA(0, 1, At, B1); PG8_BAR;
;             PG8_LDA(At, 0, 1); PG8_STAGE(PG8_SA(0, 0), a2, voffA);
;             PG8_BAR; PG8_WAIT_L(0); PG8_MMA(1, 0, At, B0); PG8_BAR; PG8_SCHED;
.LBB0_118:
	s_ashr_i32 s55, s54, 31
	v_cmp_lt_i64_e32 vcc, s[56:57], v[142:143]
	s_lshl_b64 s[56:57], s[54:55], 19
	s_add_u32 s9, s52, s56
	s_addc_u32 s31, s53, s57
	s_and_b64 s[56:57], vcc, exec
	s_cselect_b32 s57, s31, s63
	s_cselect_b32 s56, s9, s62
	s_ashr_i32 s31, s30, 31
	s_lshl_b64 s[58:59], s[30:31], 19
	s_add_u32 s9, s92, s58
	s_addc_u32 s31, s93, s59
	s_and_b64 s[58:59], vcc, exec
	s_cselect_b32 s59, s31, s65
	s_cselect_b32 s58, s9, s64
	s_add_u32 s62, s62, 0x40080
	s_addc_u32 s63, s63, 0
	s_add_u32 s9, s64, 0x100
	s_addc_u32 s31, s65, 0
	s_mov_b32 s33, -2
	s_add_u32 s55, s62, 0xfffc0080
	s_addc_u32 s61, s63, -1
	s_cmp_eq_u32 s33, 12
	s_cselect_b32 s67, s57, s61
	s_cselect_b32 s66, s56, s55
	s_cselect_b32 s65, s59, s31
	s_cselect_b32 s64, s58, s9
	ds_read_b128 v[146:149], v154
	ds_read_b128 v[158:161], v154 offset:1024
	ds_read_b128 v[162:165], v154 offset:2048
	ds_read_b128 v[166:169], v154 offset:3072
	ds_read_b128 v[170:173], v155
	ds_read_b128 v[174:177], v155 offset:1024
	ds_read_b128 v[178:181], v155 offset:2048
	ds_read_b128 v[182:185], v155 offset:3072
	ds_read_b128 v[186:189], v155 offset:4096
	ds_read_b128 v[190:193], v155 offset:5120
	ds_read_b128 v[194:197], v155 offset:6144
	ds_read_b128 v[198:201], v155 offset:7168
	ds_read_b128 v[202:205], v156
	ds_read_b128 v[206:209], v156 offset:1024
	ds_read_b128 v[210:213], v156 offset:2048
	ds_read_b128 v[214:217], v156 offset:3072
	s_add_i32 m0, s68, 0xc000
	v_lshl_add_u64 v[242:243], s[62:63], 0, v[138:139]
	global_load_lds_dwordx4 v[242:243], off
	s_add_i32 m0, s68, 0xe000
	v_lshl_add_u64 v[242:243], s[62:63], 0, v[140:141]
	global_load_lds_dwordx4 v[242:243], off
	s_waitcnt vmcnt(8) lgkmcnt(0)
	s_barrier
	v_mfma_f32_16x16x32_bf16 v[124:127], v[146:149], v[170:173], 0
	v_mfma_f32_16x16x32_bf16 v[120:123], v[162:165], v[170:173], 0
	v_mfma_f32_16x16x32_bf16 v[108:111], v[146:149], v[178:181], 0
	v_mfma_f32_16x16x32_bf16 v[104:107], v[162:165], v[178:181], 0
	v_mfma_f32_16x16x32_bf16 v[92:95], v[146:149], v[186:189], 0
	v_mfma_f32_16x16x32_bf16 v[88:91], v[162:165], v[186:189], 0
	v_mfma_f32_16x16x32_bf16 v[76:79], v[146:149], v[194:197], 0
	v_mfma_f32_16x16x32_bf16 v[72:75], v[162:165], v[194:197], 0
	v_mfma_f32_16x16x32_bf16 v[124:127], v[158:161], v[174:177], v[124:127]
	v_mfma_f32_16x16x32_bf16 v[120:123], v[166:169], v[174:177], v[120:123]
	v_mfma_f32_16x16x32_bf16 v[108:111], v[158:161], v[182:185], v[108:111]
	v_mfma_f32_16x16x32_bf16 v[104:107], v[166:169], v[182:185], v[104:107]
	v_mfma_f32_16x16x32_bf16 v[92:95], v[158:161], v[190:193], v[92:95]
	v_mfma_f32_16x16x32_bf16 v[88:91], v[166:169], v[190:193], v[88:91]
	v_mfma_f32_16x16x32_bf16 v[76:79], v[158:161], v[198:201], v[76:79]
	v_mfma_f32_16x16x32_bf16 v[72:75], v[166:169], v[198:201], v[72:75]
	v_mfma_f32_16x16x32_bf16 v[116:119], v[202:205], v[170:173], 0
	v_mfma_f32_16x16x32_bf16 v[112:115], v[210:213], v[170:173], 0
	v_mfma_f32_16x16x32_bf16 v[100:103], v[202:205], v[178:181], 0
	v_mfma_f32_16x16x32_bf16 v[96:99], v[210:213], v[178:181], 0
	v_mfma_f32_16x16x32_bf16 v[84:87], v[202:205], v[186:189], 0
	v_mfma_f32_16x16x32_bf16 v[80:83], v[210:213], v[186:189], 0
	v_mfma_f32_16x16x32_bf16 v[68:71], v[202:205], v[194:197], 0
	v_mfma_f32_16x16x32_bf16 v[64:67], v[210:213], v[194:197], 0
	v_mfma_f32_16x16x32_bf16 v[116:119], v[206:209], v[174:177], v[116:119]
	v_mfma_f32_16x16x32_bf16 v[112:115], v[214:217], v[174:177], v[112:115]
	v_mfma_f32_16x16x32_bf16 v[100:103], v[206:209], v[182:185], v[100:103]
	v_mfma_f32_16x16x32_bf16 v[96:99], v[214:217], v[182:185], v[96:99]
	v_mfma_f32_16x16x32_bf16 v[84:87], v[206:209], v[190:193], v[84:87]
	v_mfma_f32_16x16x32_bf16 v[80:83], v[214:217], v[190:193], v[80:83]
	v_mfma_f32_16x16x32_bf16 v[68:71], v[206:209], v[198:201], v[68:71]
	v_mfma_f32_16x16x32_bf16 v[64:67], v[214:217], v[198:201], v[64:67]
	s_barrier
	ds_read_b128 v[170:173], v155 offset:16384
	ds_read_b128 v[174:177], v155 offset:17408
	ds_read_b128 v[178:181], v155 offset:18432
	ds_read_b128 v[182:185], v155 offset:19456
	ds_read_b128 v[186:189], v155 offset:20480
	ds_read_b128 v[190:193], v155 offset:21504
	ds_read_b128 v[194:197], v155 offset:22528
	ds_read_b128 v[198:201], v155 offset:23552
	s_add_i32 s55, s78, s35
	s_mov_b32 m0, s55
	v_lshl_add_u64 v[218:219], s[64:65], 0, v[132:133]
	global_load_lds_dwordx4 v[218:219], off
	s_add_i32 m0, s55, 0x2000
	v_lshl_add_u64 v[220:221], s[64:65], 0, v[136:137]
	global_load_lds_dwordx4 v[220:221], off
	s_mov_b32 m0, s68
	v_lshl_add_u64 v[222:223], s[66:67], 0, v[130:131]
	global_load_lds_dwordx4 v[222:223], off
	s_mov_b32 m0, s69
	v_lshl_add_u64 v[224:225], s[66:67], 0, v[134:135]
	global_load_lds_dwordx4 v[224:225], off
	s_add_u32 s82, s64, 0x40000
	s_addc_u32 s83, s65, 0
	s_add_i32 s55, s79, s35
	s_mov_b32 m0, s55
	v_lshl_add_u64 v[240:241], s[82:83], 0, v[132:133]
	global_load_lds_dwordx4 v[240:241], off
	s_add_i32 m0, s55, 0x2000
	v_lshl_add_u64 v[240:241], s[82:83], 0, v[136:137]
	global_load_lds_dwordx4 v[240:241], off
	s_waitcnt vmcnt(8) lgkmcnt(0)
	s_barrier
; #define PG8_STAGE(bufoff, gbase, voff) do { _Pragma("unroll") for (int _i = 0; _i < 2; ++_i) \
;         __builtin_amdgcn_global_load_lds((const unsigned*)((const char*)(gbase) + (voff)[_i]), (LAS unsigned*)(lds + (bufoff) + ldsw + _i * 8192), 16, 0, 0); } while (0)
; #define PG8_LDA(dst, b, h) do { _Pragma("unroll") for (int m = 0; m < 4; ++m) _Pragma("unroll") for (int k = 0; k < 2; ++k) dst[m][k] = *(const LAS bf16x8*)(lds + PG8_SA(b, h) + aoff + m * 2048 + k * 1024); } while (0)
; #define PG8_LDB(dst, b, h) do { _Pragma("unroll") for (int n = 0; n < 2; ++n) _Pragma("unroll") for (int k = 0; k < 2; ++k) dst[n][k] = *(const LAS bf16x8*)(lds + PG8_SB(b, h) + boff + n * 2048 + k * 1024); } while (0)
; #define PG8_MMA(ai, bj, At, Bt) do { __builtin_amdgcn_s_setprio(1); _Pragma("unroll") for (int m = 0; m < 4; ++m) _Pragma("unroll") for (int n = 0; n < 2; ++n) _Pragma("unroll") for (int k = 0; k < 2; ++k) \
;         acc[ai][bj][m][n] = __builtin_amdgcn_mfma_f32_16x16x32_bf16(Bt[n][k], At[m][k], acc[ai][bj][m][n], 0, 0, 0); __builtin_amdgcn_s_setprio(0); } while (0)
; #define PG8_WAIT_V(n) asm volatile("s_waitcnt vmcnt(" #n ")" ::: "memory")
; #define PG8_WAIT_L(n) asm volatile("s_waitcnt lgkmcnt(" #n ")" ::: "memory")
; #define PG8_BAR __builtin_amdgcn_s_barrier()
; #define PG8_SCHED __builtin_amdgcn_sched_barrier(0)
; template <class Epi>
; __device__ __forceinline__ void gemm_phase(LAS unsigned char* lds, const Gemm g, const StaticOrder& S, const Epi& E) {
;     ...
;             PG8_BAR; PG8_WAIT_L(0); PG8_MMA(1, 0, At, B0); PG8_BAR; PG8_SCHED;
;             PG8_STAGE(PG8_SB(0, 1), b2 + hstepB, voffB);
;             PG8_WAIT_V(6); PG8_BAR; PG8_MMA(1, 1, At, B1); PG8_BAR;
;             PG8_LDB(B0, 1, 0); PG8_SCHED; PG8_LDA(At, 1, 0); PG8_STAGE(PG8_SA(0, 1), a2 + hstepA, voffA);
;             PG8_WAIT_L(8); PG8_BAR; PG8_WAIT_L(0); PG8_MMA(0, 0, At, B0); PG8_BAR; PG8_SCHED;
;             PG8_LDB(B1, 1, 1); PG8_STAGE(PG8_SB(1, 0), b3, voffB);
;             PG8_BAR; PG8_WAIT_L(0); PG8_MMA(0, 1, At, B1); PG8_BAR;
	v_mfma_f32_16x16x32_bf16 v[60:63], v[146:149], v[170:173], 0
	v_mfma_f32_16x16x32_bf16 v[56:59], v[162:165], v[170:173], 0
	v_mfma_f32_16x16x32_bf16 v[44:47], v[146:149], v[178:181], 0
	v_mfma_f32_16x16x32_bf16 v[40:43], v[162:165], v[178:181], 0
	v_mfma_f32_16x16x32_bf16 v[28:31], v[146:149], v[186:189], 0
	v_mfma_f32_16x16x32_bf16 v[24:27], v[162:165], v[186:189], 0
	v_mfma_f32_16x16x32_bf16 v[12:15], v[146:149], v[194:197], 0
	v_mfma_f32_16x16x32_bf16 v[8:11], v[162:165], v[194:197], 0
	v_mfma_f32_16x16x32_bf16 v[60:63], v[158:161], v[174:177], v[60:63]
	v_mfma_f32_16x16x32_bf16 v[56:59], v[166:169], v[174:177], v[56:59]
	v_mfma_f32_16x16x32_bf16 v[44:47], v[158:161], v[182:185], v[44:47]
	v_mfma_f32_16x16x32_bf16 v[40:43], v[166:169], v[182:185], v[40:43]
	v_mfma_f32_16x16x32_bf16 v[28:31], v[158:161], v[190:193], v[28:31]
	v_mfma_f32_16x16x32_bf16 v[24:27], v[166:169], v[190:193], v[24:27]
	v_mfma_f32_16x16x32_bf16 v[12:15], v[158:161], v[198:201], v[12:15]
	v_mfma_f32_16x16x32_bf16 v[8:11], v[166:169], v[198:201], v[8:11]
	v_mfma_f32_16x16x32_bf16 v[52:55], v[202:205], v[170:173], 0
	v_mfma_f32_16x16x32_bf16 v[48:51], v[210:213], v[170:173], 0
	v_mfma_f32_16x16x32_bf16 v[36:39], v[202:205], v[178:181], 0
	v_mfma_f32_16x16x32_bf16 v[32:35], v[210:213], v[178:181], 0
	v_mfma_f32_16x16x32_bf16 v[20:23], v[202:205], v[186:189], 0
	v_mfma_f32_16x16x32_bf16 v[16:19], v[210:213], v[186:189], 0
	v_mfma_f32_16x16x32_bf16 v[4:7], v[202:205], v[194:197], 0
	v_mfma_f32_16x16x32_bf16 v[0:3], v[210:213], v[194:197], 0
	v_mfma_f32_16x16x32_bf16 v[52:55], v[206:209], v[174:177], v[52:55]
	v_mfma_f32_16x16x32_bf16 v[48:51], v[214:217], v[174:177], v[48:51]
	v_mfma_f32_16x16x32_bf16 v[36:39], v[206:209], v[182:185], v[36:39]
	v_mfma_f32_16x16x32_bf16 v[32:35], v[214:217], v[182:185], v[32:35]
	v_mfma_f32_16x16x32_bf16 v[20:23], v[206:209], v[190:193], v[20:23]
	v_mfma_f32_16x16x32_bf16 v[16:19], v[214:217], v[190:193], v[16:19]
	v_mfma_f32_16x16x32_bf16 v[4:7], v[206:209], v[198:201], v[4:7]
	v_mfma_f32_16x16x32_bf16 v[0:3], v[214:217], v[198:201], v[0:3]
	s_barrier
	s_add_i32 s55, 0, 0x18000
	v_add_u32_e32 v157, s55, v152
	ds_read_b128 v[146:149], v157
	ds_read_b128 v[158:161], v157 offset:1024
	ds_read_b128 v[162:165], v157 offset:2048
	ds_read_b128 v[166:169], v157 offset:3072
	ds_read_b128 v[170:173], v155 offset:32768
	ds_read_b128 v[174:177], v155 offset:33792
	ds_read_b128 v[178:181], v155 offset:34816
	ds_read_b128 v[182:185], v155 offset:35840
	ds_read_b128 v[186:189], v155 offset:36864
	ds_read_b128 v[190:193], v155 offset:37888
	ds_read_b128 v[194:197], v155 offset:38912
	ds_read_b128 v[198:201], v155 offset:39936
	s_add_i32 s98, 0, 0x1c000
	v_add_u32_e32 v246, s98, v152
	ds_read_b128 v[202:205], v246
	ds_read_b128 v[206:209], v246 offset:1024
	ds_read_b128 v[210:213], v246 offset:2048
	ds_read_b128 v[214:217], v246 offset:3072
	s_add_u32 s66, s66, 0x40000
	s_addc_u32 s67, s67, 0
	s_mov_b32 m0, s70
	v_lshl_add_u64 v[244:245], s[66:67], 0, v[130:131]
	global_load_lds_dwordx4 v[244:245], off
	s_mov_b32 m0, s71
	v_lshl_add_u64 v[244:245], s[66:67], 0, v[134:135]
	global_load_lds_dwordx4 v[244:245], off
	s_waitcnt vmcnt(8) lgkmcnt(0)
	s_barrier
	v_mfma_f32_16x16x32_bf16 v[124:127], v[146:149], v[170:173], v[124:127]
	v_mfma_f32_16x16x32_bf16 v[120:123], v[162:165], v[170:173], v[120:123]
	v_mfma_f32_16x16x32_bf16 v[108:111], v[146:149], v[178:181], v[108:111]
	v_mfma_f32_16x16x32_bf16 v[104:107], v[162:165], v[178:181], v[104:107]
	v_mfma_f32_16x16x32_bf16 v[92:95], v[146:149], v[186:189], v[92:95]
	v_mfma_f32_16x16x32_bf16 v[88:91], v[162:165], v[186:189], v[88:91]
	v_mfma_f32_16x16x32_bf16 v[76:79], v[146:149], v[194:197], v[76:79]
	v_mfma_f32_16x16x32_bf16 v[72:75], v[162:165], v[194:197], v[72:75]
	v_mfma_f32_16x16x32_bf16 v[124:127], v[158:161], v[174:177], v[124:127]
	v_mfma_f32_16x16x32_bf16 v[120:123], v[166:169], v[174:177], v[120:123]
	v_mfma_f32_16x16x32_bf16 v[108:111], v[158:161], v[182:185], v[108:111]
	v_mfma_f32_16x16x32_bf16 v[104:107], v[166:169], v[182:185], v[104:107]
	v_mfma_f32_16x16x32_bf16 v[92:95], v[158:161], v[190:193], v[92:95]
	v_mfma_f32_16x16x32_bf16 v[88:91], v[166:169], v[190:193], v[88:91]
	v_mfma_f32_16x16x32_bf16 v[76:79], v[158:161], v[198:201], v[76:79]
	v_mfma_f32_16x16x32_bf16 v[72:75], v[166:169], v[198:201], v[72:75]
	v_mfma_f32_16x16x32_bf16 v[116:119], v[202:205], v[170:173], v[116:119]
	v_mfma_f32_16x16x32_bf16 v[112:115], v[210:213], v[170:173], v[112:115]
	v_mfma_f32_16x16x32_bf16 v[100:103], v[202:205], v[178:181], v[100:103]
	v_mfma_f32_16x16x32_bf16 v[96:99], v[210:213], v[178:181], v[96:99]
	v_mfma_f32_16x16x32_bf16 v[84:87], v[202:205], v[186:189], v[84:87]
	v_mfma_f32_16x16x32_bf16 v[80:83], v[210:213], v[186:189], v[80:83]
	v_mfma_f32_16x16x32_bf16 v[68:71], v[202:205], v[194:197], v[68:71]
	v_mfma_f32_16x16x32_bf16 v[64:67], v[210:213], v[194:197], v[64:67]
	v_mfma_f32_16x16x32_bf16 v[116:119], v[206:209], v[174:177], v[116:119]
	v_mfma_f32_16x16x32_bf16 v[112:115], v[214:217], v[174:177], v[112:115]
	v_mfma_f32_16x16x32_bf16 v[100:103], v[206:209], v[182:185], v[100:103]
	v_mfma_f32_16x16x32_bf16 v[96:99], v[214:217], v[182:185], v[96:99]
	v_mfma_f32_16x16x32_bf16 v[84:87], v[206:209], v[190:193], v[84:87]
	v_mfma_f32_16x16x32_bf16 v[80:83], v[214:217], v[190:193], v[80:83]
	v_mfma_f32_16x16x32_bf16 v[68:71], v[206:209], v[198:201], v[68:71]
	v_mfma_f32_16x16x32_bf16 v[64:67], v[214:217], v[198:201], v[64:67]
	s_barrier
; #define PG8_STAGE(bufoff, gbase, voff) do { _Pragma("unroll") for (int _i = 0; _i < 2; ++_i) \
;         __builtin_amdgcn_global_load_lds((const unsigned*)((const char*)(gbase) + (voff)[_i]), (LAS unsigned*)(lds + (bufoff) + ldsw + _i * 8192), 16, 0, 0); } while (0)
; #define PG8_LDA(dst, b, h) do { _Pragma("unroll") for (int m = 0; m < 4; ++m) _Pragma("unroll") for (int k = 0; k < 2; ++k) dst[m][k] = *(const LAS bf16x8*)(lds + PG8_SA(b, h) + aoff + m * 2048 + k * 1024); } while (0)
; #define PG8_MMA(ai, bj, At, Bt) do { __builtin_amdgcn_s_setprio(1); _Pragma("unroll") for (int m = 0; m < 4; ++m) _Pragma("unroll") for (int n = 0; n < 2; ++n) _Pragma("unroll") for (int k = 0; k < 2; ++k) \
;         acc[ai][bj][m][n] = __builtin_amdgcn_mfma_f32_16x16x32_bf16(Bt[n][k], At[m][k], acc[ai][bj][m][n], 0, 0, 0); __builtin_amdgcn_s_setprio(0); } while (0)
; #define PG8_WAIT_V(n) asm volatile("s_waitcnt vmcnt(" #n ")" ::: "memory")
; #define PG8_WAIT_L(n) asm volatile("s_waitcnt lgkmcnt(" #n ")" ::: "memory")
; #define PG8_BAR __builtin_amdgcn_s_barrier()
; #define PG8_SCHED __builtin_amdgcn_sched_barrier(0)
; template <class Epi>
; __device__ __forceinline__ void gemm_phase(LAS unsigned char* lds, const Gemm g, const StaticOrder& S, const Epi& E) {
;     ...
;             PG8_LDA(At, 1, 1); PG8_STAGE(PG8_SA(1, 0), a3, voffA);
;             PG8_BAR; PG8_WAIT_L(0); PG8_MMA(1, 0, At, B0); PG8_BAR; PG8_SCHED;
;             PG8_STAGE(PG8_SB(1, 1), b3 + hstepB, voffB);
;             PG8_WAIT_V(6); PG8_BAR; PG8_MMA(1, 1, At, B1); PG8_BAR;
	ds_read_b128 v[170:173], v155 offset:49152
	ds_read_b128 v[174:177], v155 offset:50176
	ds_read_b128 v[178:181], v155 offset:51200
	ds_read_b128 v[182:185], v155 offset:52224
	ds_read_b128 v[186:189], v155 offset:53248
	ds_read_b128 v[190:193], v155 offset:54272
	ds_read_b128 v[194:197], v155 offset:55296
	ds_read_b128 v[198:201], v155 offset:56320
	s_add_i32 s55, s55, s35
	s_mov_b32 m0, s55
	v_lshl_add_u64 v[218:219], v[218:219], 0, s[28:29]
	global_load_lds_dwordx4 v[218:219], off
	s_add_i32 m0, s55, 0x2000
	v_lshl_add_u64 v[218:219], v[220:221], 0, s[28:29]
	global_load_lds_dwordx4 v[218:219], off
	s_mov_b32 m0, s73
	v_lshl_add_u64 v[218:219], v[222:223], 0, s[28:29]
	global_load_lds_dwordx4 v[218:219], off
	s_mov_b32 m0, s74
	v_lshl_add_u64 v[218:219], v[224:225], 0, s[28:29]
	global_load_lds_dwordx4 v[218:219], off
	s_add_u32 s64, s64, 0x40080
	s_addc_u32 s65, s65, 0
	s_add_i32 s55, s98, s35
	s_mov_b32 m0, s55
	v_lshl_add_u64 v[240:241], s[64:65], 0, v[132:133]
	global_load_lds_dwordx4 v[240:241], off
	s_add_i32 m0, s55, 0x2000
	v_lshl_add_u64 v[240:241], s[64:65], 0, v[136:137]
	global_load_lds_dwordx4 v[240:241], off
	s_waitcnt vmcnt(8) lgkmcnt(0)
	s_barrier
	v_mfma_f32_16x16x32_bf16 v[60:63], v[146:149], v[170:173], v[60:63]
	v_mfma_f32_16x16x32_bf16 v[56:59], v[162:165], v[170:173], v[56:59]
	v_mfma_f32_16x16x32_bf16 v[44:47], v[146:149], v[178:181], v[44:47]
	v_mfma_f32_16x16x32_bf16 v[40:43], v[162:165], v[178:181], v[40:43]
	v_mfma_f32_16x16x32_bf16 v[28:31], v[146:149], v[186:189], v[28:31]
	v_mfma_f32_16x16x32_bf16 v[24:27], v[162:165], v[186:189], v[24:27]
	v_mfma_f32_16x16x32_bf16 v[12:15], v[146:149], v[194:197], v[12:15]
	v_mfma_f32_16x16x32_bf16 v[8:11], v[162:165], v[194:197], v[8:11]
	v_mfma_f32_16x16x32_bf16 v[60:63], v[158:161], v[174:177], v[60:63]
	v_mfma_f32_16x16x32_bf16 v[56:59], v[166:169], v[174:177], v[56:59]
	v_mfma_f32_16x16x32_bf16 v[44:47], v[158:161], v[182:185], v[44:47]
	v_mfma_f32_16x16x32_bf16 v[40:43], v[166:169], v[182:185], v[40:43]
	v_mfma_f32_16x16x32_bf16 v[28:31], v[158:161], v[190:193], v[28:31]
	v_mfma_f32_16x16x32_bf16 v[24:27], v[166:169], v[190:193], v[24:27]
	v_mfma_f32_16x16x32_bf16 v[12:15], v[158:161], v[198:201], v[12:15]
	v_mfma_f32_16x16x32_bf16 v[8:11], v[166:169], v[198:201], v[8:11]
	v_mfma_f32_16x16x32_bf16 v[52:55], v[202:205], v[170:173], v[52:55]
	v_mfma_f32_16x16x32_bf16 v[48:51], v[210:213], v[170:173], v[48:51]
	v_mfma_f32_16x16x32_bf16 v[36:39], v[202:205], v[178:181], v[36:39]
	v_mfma_f32_16x16x32_bf16 v[32:35], v[210:213], v[178:181], v[32:35]
	v_mfma_f32_16x16x32_bf16 v[20:23], v[202:205], v[186:189], v[20:23]
	v_mfma_f32_16x16x32_bf16 v[16:19], v[210:213], v[186:189], v[16:19]
	v_mfma_f32_16x16x32_bf16 v[4:7], v[202:205], v[194:197], v[4:7]
	v_mfma_f32_16x16x32_bf16 v[0:3], v[210:213], v[194:197], v[0:3]
	v_mfma_f32_16x16x32_bf16 v[52:55], v[206:209], v[174:177], v[52:55]
	v_mfma_f32_16x16x32_bf16 v[48:51], v[214:217], v[174:177], v[48:51]
	v_mfma_f32_16x16x32_bf16 v[36:39], v[206:209], v[182:185], v[36:39]
	v_mfma_f32_16x16x32_bf16 v[32:35], v[214:217], v[182:185], v[32:35]
	v_mfma_f32_16x16x32_bf16 v[20:23], v[206:209], v[190:193], v[20:23]
	v_mfma_f32_16x16x32_bf16 v[16:19], v[214:217], v[190:193], v[16:19]
	v_mfma_f32_16x16x32_bf16 v[4:7], v[206:209], v[198:201], v[4:7]
	v_mfma_f32_16x16x32_bf16 v[0:3], v[214:217], v[198:201], v[0:3]
	s_add_i32 s33, s33, 2
	s_add_u32 s62, s62, 0x100
	s_addc_u32 s63, s63, 0
	s_add_u32 s9, s9, 0x100
	s_addc_u32 s31, s31, 0
	s_cmp_gt_u32 s33, 13
	s_barrier

; #define PG8_STAGE(bufoff, gbase, voff) do { _Pragma("unroll") for (int _i = 0; _i < 2; ++_i) \
;         __builtin_amdgcn_global_load_lds((const unsigned*)((const char*)(gbase) + (voff)[_i]), (LAS unsigned*)(lds + (bufoff) + ldsw + _i * 8192), 16, 0, 0); } while (0)
; #define PG8_LDA(dst, b, h) do { _Pragma("unroll") for (int m = 0; m < 4; ++m) _Pragma("unroll") for (int k = 0; k < 2; ++k) dst[m][k] = *(const LAS bf16x8*)(lds + PG8_SA(b, h) + aoff + m * 2048 + k * 1024); } while (0)
; #define PG8_LDB(dst, b, h) do { _Pragma("unroll") for (int n = 0; n < 2; ++n) _Pragma("unroll") for (int k = 0; k < 2; ++k) dst[n][k] = *(const LAS bf16x8*)(lds + PG8_SB(b, h) + boff + n * 2048 + k * 1024); } while (0)
; #define PG8_MMA(ai, bj, At, Bt) do { __builtin_amdgcn_s_setprio(1); _Pragma("unroll") for (int m = 0; m < 4; ++m) _Pragma("unroll") for (int n = 0; n < 2; ++n) _Pragma("unroll") for (int k = 0; k < 2; ++k) \
;         acc[ai][bj][m][n] = __builtin_amdgcn_mfma_f32_16x16x32_bf16(Bt[n][k], At[m][k], acc[ai][bj][m][n], 0, 0, 0); __builtin_amdgcn_s_setprio(0); } while (0)
; #define PG8_BAR __builtin_amdgcn_s_barrier()
; template <class Epi>
; __device__ __forceinline__ void gemm_phase(LAS unsigned char* lds, const Gemm g, const StaticOrder& S, const Epi& E) {
;     ...
;         const char* nA = has_next ? (const char*)g.A + (size_t)nxt.pm * tstepA + (size_t)nxt.kt0 * kstep : cA; const char* nB = has_next ? (const char*)g.Bt + (size_t)nxt.pn * tstepB + (size_t)nxt.kt0 * kstep : cB;
;         const int nt = cur.nkt;
;         for (int t = 0; t < nt; t += 2) {
;             const bool last = (t == nt - 2);
;             const char* a1 = cA + (size_t)(t + 1) * kstep;
;             const char* a2 = last ? nA : cA + (size_t)(t + 2) * kstep; const char* b2 = last ? nB : cB + (size_t)(t + 2) * kstep;
;             const char* a3 = a2 + kstep; const char* b3 = b2 + kstep;
;             PG8_LDB(B0, 0, 0); PG8_SCHED; PG8_LDA(At, 0, 0); PG8_STAGE(PG8_SA(1, 1), a1 + hstepA, voffA);
;             PG8_WAIT_L(8); PG8_BAR; PG8_WAIT_L(0); PG8_MMA(0, 0, At, B0); PG8_BAR; PG8_SCHED;
;             PG8_LDB(B1, 0, 1); PG8_STAGE(PG8_SB(0, 0), b2, voffB);
;             PG8_BAR; PG8_WAIT_L(0); PG8_MMA(0, 1, At, B1); PG8_BAR;
;             PG8_LDA(At, 0, 1); PG8_STAGE(PG8_SA(0, 0), a2, voffA);
;             PG8_BAR; PG8_WAIT_L(0); PG8_MMA(1, 0, At, B0); PG8_BAR; PG8_SCHED;
.LBB0_455:
	s_add_i32 s21, s84, -2
	s_add_u32 s64, s64, 0x40080
	s_addc_u32 s65, s65, 0
	s_add_u32 s31, s66, 0x100
	s_addc_u32 s57, s67, 0
	s_mov_b32 s59, 0
	s_add_i32 s85, s59, 2
	s_add_u32 s66, s64, 0xfffc0080
	s_addc_u32 s67, s65, -1
	s_cmp_eq_u32 s21, s59
	s_cselect_b32 s69, s63, s67
	s_cselect_b32 s68, s62, s66
	s_cselect_b32 s67, s1, s57
	s_cselect_b32 s66, s0, s31
	ds_read_b128 v[144:147], v158
	ds_read_b128 v[148:151], v158 offset:1024
	ds_read_b128 v[162:165], v158 offset:2048
	ds_read_b128 v[166:169], v158 offset:3072
	ds_read_b128 v[170:173], v159
	ds_read_b128 v[174:177], v159 offset:1024
	ds_read_b128 v[178:181], v159 offset:2048
	ds_read_b128 v[182:185], v159 offset:3072
	ds_read_b128 v[186:189], v159 offset:4096
	ds_read_b128 v[190:193], v159 offset:5120
	ds_read_b128 v[194:197], v159 offset:6144
	ds_read_b128 v[198:201], v159 offset:7168
	ds_read_b128 v[202:205], v160
	ds_read_b128 v[206:209], v160 offset:1024
	ds_read_b128 v[210:213], v160 offset:2048
	ds_read_b128 v[214:217], v160 offset:3072
	s_add_i32 m0, s35, 0xc000
	v_lshl_add_u64 v[152:153], s[64:65], 0, v[138:139]
	global_load_lds_dwordx4 v[152:153], off
	s_add_i32 m0, s35, 0xe000
	v_lshl_add_u64 v[152:153], s[64:65], 0, v[140:141]
	global_load_lds_dwordx4 v[152:153], off
	s_waitcnt vmcnt(8) lgkmcnt(0)
	s_barrier
	v_mfma_f32_16x16x32_bf16 v[124:127], v[144:147], v[170:173], 0
	v_mfma_f32_16x16x32_bf16 v[120:123], v[162:165], v[170:173], 0
	v_mfma_f32_16x16x32_bf16 v[116:119], v[144:147], v[178:181], 0
	v_mfma_f32_16x16x32_bf16 v[108:111], v[162:165], v[178:181], 0
	v_mfma_f32_16x16x32_bf16 v[100:103], v[144:147], v[186:189], 0
	v_mfma_f32_16x16x32_bf16 v[92:95], v[162:165], v[186:189], 0
	v_mfma_f32_16x16x32_bf16 v[84:87], v[144:147], v[194:197], 0
	v_mfma_f32_16x16x32_bf16 v[76:79], v[162:165], v[194:197], 0
	v_mfma_f32_16x16x32_bf16 v[124:127], v[148:151], v[174:177], v[124:127]
	v_mfma_f32_16x16x32_bf16 v[120:123], v[166:169], v[174:177], v[120:123]
	v_mfma_f32_16x16x32_bf16 v[116:119], v[148:151], v[182:185], v[116:119]
	v_mfma_f32_16x16x32_bf16 v[108:111], v[166:169], v[182:185], v[108:111]
	v_mfma_f32_16x16x32_bf16 v[100:103], v[148:151], v[190:193], v[100:103]
	v_mfma_f32_16x16x32_bf16 v[92:95], v[166:169], v[190:193], v[92:95]
	v_mfma_f32_16x16x32_bf16 v[84:87], v[148:151], v[198:201], v[84:87]
	v_mfma_f32_16x16x32_bf16 v[76:79], v[166:169], v[198:201], v[76:79]
	v_mfma_f32_16x16x32_bf16 v[112:115], v[202:205], v[170:173], 0
	v_mfma_f32_16x16x32_bf16 v[104:107], v[210:213], v[170:173], 0
	v_mfma_f32_16x16x32_bf16 v[96:99], v[202:205], v[178:181], 0
	v_mfma_f32_16x16x32_bf16 v[88:91], v[210:213], v[178:181], 0
	v_mfma_f32_16x16x32_bf16 v[80:83], v[202:205], v[186:189], 0
	v_mfma_f32_16x16x32_bf16 v[72:75], v[210:213], v[186:189], 0
	v_mfma_f32_16x16x32_bf16 v[68:71], v[202:205], v[194:197], 0
	v_mfma_f32_16x16x32_bf16 v[64:67], v[210:213], v[194:197], 0
	v_mfma_f32_16x16x32_bf16 v[112:115], v[206:209], v[174:177], v[112:115]
	v_mfma_f32_16x16x32_bf16 v[104:107], v[214:217], v[174:177], v[104:107]
	v_mfma_f32_16x16x32_bf16 v[96:99], v[206:209], v[182:185], v[96:99]
	v_mfma_f32_16x16x32_bf16 v[88:91], v[214:217], v[182:185], v[88:91]
	v_mfma_f32_16x16x32_bf16 v[80:83], v[206:209], v[190:193], v[80:83]
	v_mfma_f32_16x16x32_bf16 v[72:75], v[214:217], v[190:193], v[72:75]
	v_mfma_f32_16x16x32_bf16 v[68:71], v[206:209], v[198:201], v[68:71]
	v_mfma_f32_16x16x32_bf16 v[64:67], v[214:217], v[198:201], v[64:67]
	s_barrier
	ds_read_b128 v[170:173], v159 offset:16384
	ds_read_b128 v[174:177], v159 offset:17408
	ds_read_b128 v[178:181], v159 offset:18432
	ds_read_b128 v[182:185], v159 offset:19456
	ds_read_b128 v[186:189], v159 offset:20480
	ds_read_b128 v[190:193], v159 offset:21504
	ds_read_b128 v[194:197], v159 offset:22528
	ds_read_b128 v[198:201], v159 offset:23552
	s_add_i32 s59, s78, s33
	s_mov_b32 m0, s59
	v_lshl_add_u64 v[152:153], s[66:67], 0, v[132:133]
	global_load_lds_dwordx4 v[152:153], off
	s_add_i32 m0, s59, 0x2000
	v_lshl_add_u64 v[218:219], s[66:67], 0, v[136:137]
	global_load_lds_dwordx4 v[218:219], off
	s_mov_b32 m0, s35
	v_lshl_add_u64 v[220:221], s[68:69], 0, v[130:131]
	global_load_lds_dwordx4 v[220:221], off
	s_mov_b32 m0, s70
	v_lshl_add_u64 v[222:223], s[68:69], 0, v[134:135]
	global_load_lds_dwordx4 v[222:223], off
	s_add_u32 s86, s66, 0x40000
	s_addc_u32 s87, s67, 0
	s_add_i32 s59, s79, s33
	s_mov_b32 m0, s59
	v_lshl_add_u64 v[240:241], s[86:87], 0, v[132:133]
	global_load_lds_dwordx4 v[240:241], off
	s_add_i32 m0, s59, 0x2000
	v_lshl_add_u64 v[240:241], s[86:87], 0, v[136:137]
	global_load_lds_dwordx4 v[240:241], off
	s_waitcnt vmcnt(8) lgkmcnt(0)
	s_barrier
; #define PG8_STAGE(bufoff, gbase, voff) do { _Pragma("unroll") for (int _i = 0; _i < 2; ++_i) \
;         __builtin_amdgcn_global_load_lds((const unsigned*)((const char*)(gbase) + (voff)[_i]), (LAS unsigned*)(lds + (bufoff) + ldsw + _i * 8192), 16, 0, 0); } while (0)
; #define PG8_LDA(dst, b, h) do { _Pragma("unroll") for (int m = 0; m < 4; ++m) _Pragma("unroll") for (int k = 0; k < 2; ++k) dst[m][k] = *(const LAS bf16x8*)(lds + PG8_SA(b, h) + aoff + m * 2048 + k * 1024); } while (0)
; #define PG8_LDB(dst, b, h) do { _Pragma("unroll") for (int n = 0; n < 2; ++n) _Pragma("unroll") for (int k = 0; k < 2; ++k) dst[n][k] = *(const LAS bf16x8*)(lds + PG8_SB(b, h) + boff + n * 2048 + k * 1024); } while (0)
; #define PG8_MMA(ai, bj, At, Bt) do { __builtin_amdgcn_s_setprio(1); _Pragma("unroll") for (int m = 0; m < 4; ++m) _Pragma("unroll") for (int n = 0; n < 2; ++n) _Pragma("unroll") for (int k = 0; k < 2; ++k) \
;         acc[ai][bj][m][n] = __builtin_amdgcn_mfma_f32_16x16x32_bf16(Bt[n][k], At[m][k], acc[ai][bj][m][n], 0, 0, 0); __builtin_amdgcn_s_setprio(0); } while (0)
; #define PG8_WAIT_V(n) asm volatile("s_waitcnt vmcnt(" #n ")" ::: "memory")
; #define PG8_WAIT_L(n) asm volatile("s_waitcnt lgkmcnt(" #n ")" ::: "memory")
; #define PG8_BAR __builtin_amdgcn_s_barrier()
; #define PG8_SCHED __builtin_amdgcn_sched_barrier(0)
; template <class Epi>
; __device__ __forceinline__ void gemm_phase(LAS unsigned char* lds, const Gemm g, const StaticOrder& S, const Epi& E) {
;     ...
;             PG8_BAR; PG8_WAIT_L(0); PG8_MMA(1, 0, At, B0); PG8_BAR; PG8_SCHED;
;             PG8_STAGE(PG8_SB(0, 1), b2 + hstepB, voffB);
;             PG8_WAIT_V(6); PG8_BAR; PG8_MMA(1, 1, At, B1); PG8_BAR;
;             PG8_LDB(B0, 1, 0); PG8_SCHED; PG8_LDA(At, 1, 0); PG8_STAGE(PG8_SA(0, 1), a2 + hstepA, voffA);
;             PG8_WAIT_L(8); PG8_BAR; PG8_WAIT_L(0); PG8_MMA(0, 0, At, B0); PG8_BAR; PG8_SCHED;
;             PG8_LDB(B1, 1, 1); PG8_STAGE(PG8_SB(1, 0), b3, voffB);
;             PG8_BAR; PG8_WAIT_L(0); PG8_MMA(0, 1, At, B1); PG8_BAR;
	v_mfma_f32_16x16x32_bf16 v[60:63], v[144:147], v[170:173], 0
	v_mfma_f32_16x16x32_bf16 v[56:59], v[162:165], v[170:173], 0
	v_mfma_f32_16x16x32_bf16 v[52:55], v[144:147], v[178:181], 0
	v_mfma_f32_16x16x32_bf16 v[44:47], v[162:165], v[178:181], 0
	v_mfma_f32_16x16x32_bf16 v[36:39], v[144:147], v[186:189], 0
	v_mfma_f32_16x16x32_bf16 v[28:31], v[162:165], v[186:189], 0
	v_mfma_f32_16x16x32_bf16 v[20:23], v[144:147], v[194:197], 0
	v_mfma_f32_16x16x32_bf16 v[12:15], v[162:165], v[194:197], 0
	v_mfma_f32_16x16x32_bf16 v[60:63], v[148:151], v[174:177], v[60:63]
	v_mfma_f32_16x16x32_bf16 v[56:59], v[166:169], v[174:177], v[56:59]
	v_mfma_f32_16x16x32_bf16 v[52:55], v[148:151], v[182:185], v[52:55]
	v_mfma_f32_16x16x32_bf16 v[44:47], v[166:169], v[182:185], v[44:47]
	v_mfma_f32_16x16x32_bf16 v[36:39], v[148:151], v[190:193], v[36:39]
	v_mfma_f32_16x16x32_bf16 v[28:31], v[166:169], v[190:193], v[28:31]
	v_mfma_f32_16x16x32_bf16 v[20:23], v[148:151], v[198:201], v[20:23]
	v_mfma_f32_16x16x32_bf16 v[12:15], v[166:169], v[198:201], v[12:15]
	v_mfma_f32_16x16x32_bf16 v[48:51], v[202:205], v[170:173], 0
	v_mfma_f32_16x16x32_bf16 v[40:43], v[210:213], v[170:173], 0
	v_mfma_f32_16x16x32_bf16 v[32:35], v[202:205], v[178:181], 0
	v_mfma_f32_16x16x32_bf16 v[24:27], v[210:213], v[178:181], 0
	v_mfma_f32_16x16x32_bf16 v[16:19], v[202:205], v[186:189], 0
	v_mfma_f32_16x16x32_bf16 v[8:11], v[210:213], v[186:189], 0
	v_mfma_f32_16x16x32_bf16 v[4:7], v[202:205], v[194:197], 0
	v_mfma_f32_16x16x32_bf16 v[0:3], v[210:213], v[194:197], 0
	v_mfma_f32_16x16x32_bf16 v[48:51], v[206:209], v[174:177], v[48:51]
	v_mfma_f32_16x16x32_bf16 v[40:43], v[214:217], v[174:177], v[40:43]
	v_mfma_f32_16x16x32_bf16 v[32:35], v[206:209], v[182:185], v[32:35]
	v_mfma_f32_16x16x32_bf16 v[24:27], v[214:217], v[182:185], v[24:27]
	v_mfma_f32_16x16x32_bf16 v[16:19], v[206:209], v[190:193], v[16:19]
	v_mfma_f32_16x16x32_bf16 v[8:11], v[214:217], v[190:193], v[8:11]
	v_mfma_f32_16x16x32_bf16 v[4:7], v[206:209], v[198:201], v[4:7]
	v_mfma_f32_16x16x32_bf16 v[0:3], v[214:217], v[198:201], v[0:3]
	s_barrier
	s_add_i32 s59, 0, 0x18000
	v_add_u32_e32 v161, s59, v156
	ds_read_b128 v[144:147], v161
	ds_read_b128 v[148:151], v161 offset:1024
	ds_read_b128 v[162:165], v161 offset:2048
	ds_read_b128 v[166:169], v161 offset:3072
	ds_read_b128 v[170:173], v159 offset:32768
	ds_read_b128 v[174:177], v159 offset:33792
	ds_read_b128 v[178:181], v159 offset:34816
	ds_read_b128 v[182:185], v159 offset:35840
	ds_read_b128 v[186:189], v159 offset:36864
	ds_read_b128 v[190:193], v159 offset:37888
	ds_read_b128 v[194:197], v159 offset:38912
	ds_read_b128 v[198:201], v159 offset:39936
	s_add_i32 s98, 0, 0x1c000
	v_add_u32_e32 v246, s98, v156
	ds_read_b128 v[202:205], v246
	ds_read_b128 v[206:209], v246 offset:1024
	ds_read_b128 v[210:213], v246 offset:2048
	ds_read_b128 v[214:217], v246 offset:3072
	s_add_u32 s68, s68, 0x40000
	s_addc_u32 s69, s69, 0
	s_mov_b32 m0, s71
	v_lshl_add_u64 v[244:245], s[68:69], 0, v[130:131]
	global_load_lds_dwordx4 v[244:245], off
	s_mov_b32 m0, s72
	v_lshl_add_u64 v[244:245], s[68:69], 0, v[134:135]
	global_load_lds_dwordx4 v[244:245], off
	s_waitcnt vmcnt(8) lgkmcnt(0)
	s_barrier
	v_mfma_f32_16x16x32_bf16 v[124:127], v[144:147], v[170:173], v[124:127]
	v_mfma_f32_16x16x32_bf16 v[120:123], v[162:165], v[170:173], v[120:123]
	v_mfma_f32_16x16x32_bf16 v[116:119], v[144:147], v[178:181], v[116:119]
	v_mfma_f32_16x16x32_bf16 v[108:111], v[162:165], v[178:181], v[108:111]
	v_mfma_f32_16x16x32_bf16 v[100:103], v[144:147], v[186:189], v[100:103]
	v_mfma_f32_16x16x32_bf16 v[92:95], v[162:165], v[186:189], v[92:95]
	v_mfma_f32_16x16x32_bf16 v[84:87], v[144:147], v[194:197], v[84:87]
	v_mfma_f32_16x16x32_bf16 v[76:79], v[162:165], v[194:197], v[76:79]
	v_mfma_f32_16x16x32_bf16 v[124:127], v[148:151], v[174:177], v[124:127]
	v_mfma_f32_16x16x32_bf16 v[120:123], v[166:169], v[174:177], v[120:123]
	v_mfma_f32_16x16x32_bf16 v[116:119], v[148:151], v[182:185], v[116:119]
	v_mfma_f32_16x16x32_bf16 v[108:111], v[166:169], v[182:185], v[108:111]
	v_mfma_f32_16x16x32_bf16 v[100:103], v[148:151], v[190:193], v[100:103]
	v_mfma_f32_16x16x32_bf16 v[92:95], v[166:169], v[190:193], v[92:95]
	v_mfma_f32_16x16x32_bf16 v[84:87], v[148:151], v[198:201], v[84:87]
	v_mfma_f32_16x16x32_bf16 v[76:79], v[166:169], v[198:201], v[76:79]
	v_mfma_f32_16x16x32_bf16 v[112:115], v[202:205], v[170:173], v[112:115]
	v_mfma_f32_16x16x32_bf16 v[104:107], v[210:213], v[170:173], v[104:107]
	v_mfma_f32_16x16x32_bf16 v[96:99], v[202:205], v[178:181], v[96:99]
	v_mfma_f32_16x16x32_bf16 v[88:91], v[210:213], v[178:181], v[88:91]
	v_mfma_f32_16x16x32_bf16 v[80:83], v[202:205], v[186:189], v[80:83]
	v_mfma_f32_16x16x32_bf16 v[72:75], v[210:213], v[186:189], v[72:75]
	v_mfma_f32_16x16x32_bf16 v[68:71], v[202:205], v[194:197], v[68:71]
	v_mfma_f32_16x16x32_bf16 v[64:67], v[210:213], v[194:197], v[64:67]
	v_mfma_f32_16x16x32_bf16 v[112:115], v[206:209], v[174:177], v[112:115]
	v_mfma_f32_16x16x32_bf16 v[104:107], v[214:217], v[174:177], v[104:107]
	v_mfma_f32_16x16x32_bf16 v[96:99], v[206:209], v[182:185], v[96:99]
	v_mfma_f32_16x16x32_bf16 v[88:91], v[214:217], v[182:185], v[88:91]
	v_mfma_f32_16x16x32_bf16 v[80:83], v[206:209], v[190:193], v[80:83]
	v_mfma_f32_16x16x32_bf16 v[72:75], v[214:217], v[190:193], v[72:75]
	v_mfma_f32_16x16x32_bf16 v[68:71], v[206:209], v[198:201], v[68:71]
	v_mfma_f32_16x16x32_bf16 v[64:67], v[214:217], v[198:201], v[64:67]
	s_barrier
; #define PG8_STAGE(bufoff, gbase, voff) do { _Pragma("unroll") for (int _i = 0; _i < 2; ++_i) \
;         __builtin_amdgcn_global_load_lds((const unsigned*)((const char*)(gbase) + (voff)[_i]), (LAS unsigned*)(lds + (bufoff) + ldsw + _i * 8192), 16, 0, 0); } while (0)
; #define PG8_LDA(dst, b, h) do { _Pragma("unroll") for (int m = 0; m < 4; ++m) _Pragma("unroll") for (int k = 0; k < 2; ++k) dst[m][k] = *(const LAS bf16x8*)(lds + PG8_SA(b, h) + aoff + m * 2048 + k * 1024); } while (0)
; #define PG8_MMA(ai, bj, At, Bt) do { __builtin_amdgcn_s_setprio(1); _Pragma("unroll") for (int m = 0; m < 4; ++m) _Pragma("unroll") for (int n = 0; n < 2; ++n) _Pragma("unroll") for (int k = 0; k < 2; ++k) \
;         acc[ai][bj][m][n] = __builtin_amdgcn_mfma_f32_16x16x32_bf16(Bt[n][k], At[m][k], acc[ai][bj][m][n], 0, 0, 0); __builtin_amdgcn_s_setprio(0); } while (0)
; #define PG8_WAIT_V(n) asm volatile("s_waitcnt vmcnt(" #n ")" ::: "memory")
; #define PG8_WAIT_L(n) asm volatile("s_waitcnt lgkmcnt(" #n ")" ::: "memory")
; #define PG8_BAR __builtin_amdgcn_s_barrier()
; #define PG8_SCHED __builtin_amdgcn_sched_barrier(0)
; template <class Epi>
; __device__ __forceinline__ void gemm_phase(LAS unsigned char* lds, const Gemm g, const StaticOrder& S, const Epi& E) {
;     ...
;             PG8_LDA(At, 1, 1); PG8_STAGE(PG8_SA(1, 0), a3, voffA);
;             PG8_BAR; PG8_WAIT_L(0); PG8_MMA(1, 0, At, B0); PG8_BAR; PG8_SCHED;
;             PG8_STAGE(PG8_SB(1, 1), b3 + hstepB, voffB);
;             PG8_WAIT_V(6); PG8_BAR; PG8_MMA(1, 1, At, B1); PG8_BAR;
	ds_read_b128 v[170:173], v159 offset:49152
	ds_read_b128 v[174:177], v159 offset:50176
	ds_read_b128 v[178:181], v159 offset:51200
	ds_read_b128 v[182:185], v159 offset:52224
	ds_read_b128 v[186:189], v159 offset:53248
	ds_read_b128 v[190:193], v159 offset:54272
	ds_read_b128 v[194:197], v159 offset:55296
	ds_read_b128 v[198:201], v159 offset:56320
	s_add_i32 s59, s59, s33
	s_mov_b32 m0, s59
	v_lshl_add_u64 v[152:153], v[152:153], 0, s[12:13]
	global_load_lds_dwordx4 v[152:153], off
	s_add_i32 m0, s59, 0x2000
	v_lshl_add_u64 v[152:153], v[218:219], 0, s[12:13]
	global_load_lds_dwordx4 v[152:153], off
	s_mov_b32 m0, s73
	v_lshl_add_u64 v[152:153], v[220:221], 0, s[12:13]
	global_load_lds_dwordx4 v[152:153], off
	s_mov_b32 m0, s74
	v_lshl_add_u64 v[152:153], v[222:223], 0, s[12:13]
	global_load_lds_dwordx4 v[152:153], off
	s_add_u32 s66, s66, 0x40080
	s_addc_u32 s67, s67, 0
	s_add_i32 s59, s98, s33
	s_mov_b32 m0, s59
	v_lshl_add_u64 v[240:241], s[66:67], 0, v[132:133]
	global_load_lds_dwordx4 v[240:241], off
	s_add_i32 m0, s59, 0x2000
	v_lshl_add_u64 v[240:241], s[66:67], 0, v[136:137]
	global_load_lds_dwordx4 v[240:241], off
	s_waitcnt vmcnt(8) lgkmcnt(0)
	s_barrier
	v_mfma_f32_16x16x32_bf16 v[60:63], v[144:147], v[170:173], v[60:63]
	v_mfma_f32_16x16x32_bf16 v[56:59], v[162:165], v[170:173], v[56:59]
	v_mfma_f32_16x16x32_bf16 v[52:55], v[144:147], v[178:181], v[52:55]
	v_mfma_f32_16x16x32_bf16 v[44:47], v[162:165], v[178:181], v[44:47]
	v_mfma_f32_16x16x32_bf16 v[36:39], v[144:147], v[186:189], v[36:39]
	v_mfma_f32_16x16x32_bf16 v[28:31], v[162:165], v[186:189], v[28:31]
	v_mfma_f32_16x16x32_bf16 v[20:23], v[144:147], v[194:197], v[20:23]
	v_mfma_f32_16x16x32_bf16 v[12:15], v[162:165], v[194:197], v[12:15]
	v_mfma_f32_16x16x32_bf16 v[60:63], v[148:151], v[174:177], v[60:63]
	v_mfma_f32_16x16x32_bf16 v[56:59], v[166:169], v[174:177], v[56:59]
	v_mfma_f32_16x16x32_bf16 v[52:55], v[148:151], v[182:185], v[52:55]
	v_mfma_f32_16x16x32_bf16 v[44:47], v[166:169], v[182:185], v[44:47]
	v_mfma_f32_16x16x32_bf16 v[36:39], v[148:151], v[190:193], v[36:39]
	v_mfma_f32_16x16x32_bf16 v[28:31], v[166:169], v[190:193], v[28:31]
	v_mfma_f32_16x16x32_bf16 v[20:23], v[148:151], v[198:201], v[20:23]
	v_mfma_f32_16x16x32_bf16 v[12:15], v[166:169], v[198:201], v[12:15]
	v_mfma_f32_16x16x32_bf16 v[48:51], v[202:205], v[170:173], v[48:51]
	v_mfma_f32_16x16x32_bf16 v[40:43], v[210:213], v[170:173], v[40:43]
	v_mfma_f32_16x16x32_bf16 v[32:35], v[202:205], v[178:181], v[32:35]
	v_mfma_f32_16x16x32_bf16 v[24:27], v[210:213], v[178:181], v[24:27]
	v_mfma_f32_16x16x32_bf16 v[16:19], v[202:205], v[186:189], v[16:19]
	v_mfma_f32_16x16x32_bf16 v[8:11], v[210:213], v[186:189], v[8:11]
	v_mfma_f32_16x16x32_bf16 v[4:7], v[202:205], v[194:197], v[4:7]
	v_mfma_f32_16x16x32_bf16 v[0:3], v[210:213], v[194:197], v[0:3]
	v_mfma_f32_16x16x32_bf16 v[48:51], v[206:209], v[174:177], v[48:51]
	v_mfma_f32_16x16x32_bf16 v[40:43], v[214:217], v[174:177], v[40:43]
	v_mfma_f32_16x16x32_bf16 v[32:35], v[206:209], v[182:185], v[32:35]
	v_mfma_f32_16x16x32_bf16 v[24:27], v[214:217], v[182:185], v[24:27]
	v_mfma_f32_16x16x32_bf16 v[16:19], v[206:209], v[190:193], v[16:19]
	v_mfma_f32_16x16x32_bf16 v[8:11], v[214:217], v[190:193], v[8:11]
	v_mfma_f32_16x16x32_bf16 v[4:7], v[206:209], v[198:201], v[4:7]
	v_mfma_f32_16x16x32_bf16 v[0:3], v[214:217], v[198:201], v[0:3]
	s_add_u32 s64, s64, 0x100
	s_addc_u32 s65, s65, 0
	s_add_u32 s31, s31, 0x100
	s_addc_u32 s57, s57, 0
	s_cmp_ge_i32 s85, s84
	s_mov_b32 s59, s85
	s_barrier

; #define PG8_STAGE(bufoff, gbase, voff) do { _Pragma("unroll") for (int _i = 0; _i < 2; ++_i) \
;         __builtin_amdgcn_global_load_lds((const unsigned*)((const char*)(gbase) + (voff)[_i]), (LAS unsigned*)(lds + (bufoff) + ldsw + _i * 8192), 16, 0, 0); } while (0)
; #define PG8_LDA(dst, b, h) do { _Pragma("unroll") for (int m = 0; m < 4; ++m) _Pragma("unroll") for (int k = 0; k < 2; ++k) dst[m][k] = *(const LAS bf16x8*)(lds + PG8_SA(b, h) + aoff + m * 2048 + k * 1024); } while (0)
; #define PG8_LDB(dst, b, h) do { _Pragma("unroll") for (int n = 0; n < 2; ++n) _Pragma("unroll") for (int k = 0; k < 2; ++k) dst[n][k] = *(const LAS bf16x8*)(lds + PG8_SB(b, h) + boff + n * 2048 + k * 1024); } while (0)
; #define PG8_MMA(ai, bj, At, Bt) do { __builtin_amdgcn_s_setprio(1); _Pragma("unroll") for (int m = 0; m < 4; ++m) _Pragma("unroll") for (int n = 0; n < 2; ++n) _Pragma("unroll") for (int k = 0; k < 2; ++k) \
;         acc[ai][bj][m][n] = __builtin_amdgcn_mfma_f32_16x16x32_bf16(Bt[n][k], At[m][k], acc[ai][bj][m][n], 0, 0, 0); __builtin_amdgcn_s_setprio(0); } while (0)
; #define PG8_BAR __builtin_amdgcn_s_barrier()
; template <class Epi>
; __device__ __forceinline__ void gemm_phase(LAS unsigned char* lds, const Gemm g, const StaticOrder& S, const Epi& E) {
;     ...
;         const char* nA = has_next ? (const char*)g.A + (size_t)nxt.pm * tstepA + (size_t)nxt.kt0 * kstep : cA; const char* nB = has_next ? (const char*)g.Bt + (size_t)nxt.pn * tstepB + (size_t)nxt.kt0 * kstep : cB;
;         const int nt = cur.nkt;
;         for (int t = 0; t < nt; t += 2) {
;             const bool last = (t == nt - 2);
;             const char* a1 = cA + (size_t)(t + 1) * kstep;
;             const char* a2 = last ? nA : cA + (size_t)(t + 2) * kstep; const char* b2 = last ? nB : cB + (size_t)(t + 2) * kstep;
;             const char* a3 = a2 + kstep; const char* b3 = b2 + kstep;
;             PG8_LDB(B0, 0, 0); PG8_SCHED; PG8_LDA(At, 0, 0); PG8_STAGE(PG8_SA(1, 1), a1 + hstepA, voffA);
;             PG8_WAIT_L(8); PG8_BAR; PG8_WAIT_L(0); PG8_MMA(0, 0, At, B0); PG8_BAR; PG8_SCHED;
;             PG8_LDB(B1, 0, 1); PG8_STAGE(PG8_SB(0, 0), b2, voffB);
;             PG8_BAR; PG8_WAIT_L(0); PG8_MMA(0, 1, At, B1); PG8_BAR;
;             PG8_LDA(At, 0, 1); PG8_STAGE(PG8_SA(0, 0), a2, voffA);
;             PG8_BAR; PG8_WAIT_L(0); PG8_MMA(1, 0, At, B0); PG8_BAR; PG8_SCHED;
.LBB0_681:
	s_ashr_i32 s39, s38, 31
	v_cmp_lt_i64_e32 vcc, s[40:41], v[148:149]
	s_lshl_b64 s[40:41], s[38:39], 19
	s_add_u32 s37, s52, s40
	s_addc_u32 s39, s53, s41
	s_and_b64 s[40:41], vcc, exec
	s_cselect_b32 s41, s39, s61
	s_cselect_b32 s40, s37, s60
	s_ashr_i32 s37, s36, 31
	s_lshl_b64 s[56:57], s[36:37], 19
	s_add_u32 s37, s54, s56
	s_addc_u32 s39, s55, s57
	s_and_b64 s[56:57], vcc, exec
	s_cselect_b32 s57, s39, s63
	s_cselect_b32 s56, s37, s62
	s_add_u32 s60, s60, 0x40080
	s_addc_u32 s61, s61, 0
	s_add_u32 s37, s62, 0x100
	s_addc_u32 s39, s63, 0
	s_mov_b32 s78, -2
	s_add_u32 s62, s60, 0xfffc0080
	s_addc_u32 s63, s61, -1
	s_cmp_eq_u32 s78, 12
	s_cselect_b32 s65, s41, s63
	s_cselect_b32 s64, s40, s62
	s_cselect_b32 s63, s57, s39
	s_cselect_b32 s62, s56, s37
	ds_read_b128 v[152:155], v159
	ds_read_b128 v[162:165], v159 offset:1024
	ds_read_b128 v[166:169], v159 offset:2048
	ds_read_b128 v[170:173], v159 offset:3072
	ds_read_b128 v[174:177], v160
	ds_read_b128 v[178:181], v160 offset:1024
	ds_read_b128 v[182:185], v160 offset:2048
	ds_read_b128 v[186:189], v160 offset:3072
	ds_read_b128 v[190:193], v160 offset:4096
	ds_read_b128 v[194:197], v160 offset:5120
	ds_read_b128 v[198:201], v160 offset:6144
	ds_read_b128 v[202:205], v160 offset:7168
	ds_read_b128 v[206:209], v161
	ds_read_b128 v[210:213], v161 offset:1024
	ds_read_b128 v[214:217], v161 offset:2048
	ds_read_b128 v[218:221], v161 offset:3072
	s_add_i32 m0, s35, 0xc000
	v_lshl_add_u64 v[242:243], s[60:61], 0, v[144:145]
	global_load_lds_dwordx4 v[242:243], off
	s_add_i32 m0, s35, 0xe000
	v_lshl_add_u64 v[242:243], s[60:61], 0, v[146:147]
	global_load_lds_dwordx4 v[242:243], off
	s_waitcnt vmcnt(8) lgkmcnt(0)
	s_barrier
	v_mfma_f32_16x16x32_bf16 v[124:127], v[152:155], v[174:177], 0
	v_mfma_f32_16x16x32_bf16 v[120:123], v[166:169], v[174:177], 0
	v_mfma_f32_16x16x32_bf16 v[116:119], v[152:155], v[182:185], 0
	v_mfma_f32_16x16x32_bf16 v[108:111], v[166:169], v[182:185], 0
	v_mfma_f32_16x16x32_bf16 v[100:103], v[152:155], v[190:193], 0
	v_mfma_f32_16x16x32_bf16 v[92:95], v[166:169], v[190:193], 0
	v_mfma_f32_16x16x32_bf16 v[84:87], v[152:155], v[198:201], 0
	v_mfma_f32_16x16x32_bf16 v[76:79], v[166:169], v[198:201], 0
	v_mfma_f32_16x16x32_bf16 v[124:127], v[162:165], v[178:181], v[124:127]
	v_mfma_f32_16x16x32_bf16 v[120:123], v[170:173], v[178:181], v[120:123]
	v_mfma_f32_16x16x32_bf16 v[116:119], v[162:165], v[186:189], v[116:119]
	v_mfma_f32_16x16x32_bf16 v[108:111], v[170:173], v[186:189], v[108:111]
	v_mfma_f32_16x16x32_bf16 v[100:103], v[162:165], v[194:197], v[100:103]
	v_mfma_f32_16x16x32_bf16 v[92:95], v[170:173], v[194:197], v[92:95]
	v_mfma_f32_16x16x32_bf16 v[84:87], v[162:165], v[202:205], v[84:87]
	v_mfma_f32_16x16x32_bf16 v[76:79], v[170:173], v[202:205], v[76:79]
	v_mfma_f32_16x16x32_bf16 v[112:115], v[206:209], v[174:177], 0
	v_mfma_f32_16x16x32_bf16 v[104:107], v[214:217], v[174:177], 0
	v_mfma_f32_16x16x32_bf16 v[96:99], v[206:209], v[182:185], 0
	v_mfma_f32_16x16x32_bf16 v[88:91], v[214:217], v[182:185], 0
	v_mfma_f32_16x16x32_bf16 v[80:83], v[206:209], v[190:193], 0
	v_mfma_f32_16x16x32_bf16 v[72:75], v[214:217], v[190:193], 0
	v_mfma_f32_16x16x32_bf16 v[68:71], v[206:209], v[198:201], 0
	v_mfma_f32_16x16x32_bf16 v[64:67], v[214:217], v[198:201], 0
	v_mfma_f32_16x16x32_bf16 v[112:115], v[210:213], v[178:181], v[112:115]
	v_mfma_f32_16x16x32_bf16 v[104:107], v[218:221], v[178:181], v[104:107]
	v_mfma_f32_16x16x32_bf16 v[96:99], v[210:213], v[186:189], v[96:99]
	v_mfma_f32_16x16x32_bf16 v[88:91], v[218:221], v[186:189], v[88:91]
	v_mfma_f32_16x16x32_bf16 v[80:83], v[210:213], v[194:197], v[80:83]
	v_mfma_f32_16x16x32_bf16 v[72:75], v[218:221], v[194:197], v[72:75]
	v_mfma_f32_16x16x32_bf16 v[68:71], v[210:213], v[202:205], v[68:71]
	v_mfma_f32_16x16x32_bf16 v[64:67], v[218:221], v[202:205], v[64:67]
	s_barrier
	ds_read_b128 v[174:177], v160 offset:16384
	ds_read_b128 v[178:181], v160 offset:17408
	ds_read_b128 v[182:185], v160 offset:18432
	ds_read_b128 v[186:189], v160 offset:19456
	ds_read_b128 v[190:193], v160 offset:20480
	ds_read_b128 v[194:197], v160 offset:21504
	ds_read_b128 v[198:201], v160 offset:22528
	ds_read_b128 v[202:205], v160 offset:23552
	s_add_i32 s79, s75, s33
	s_mov_b32 m0, s79
	v_lshl_add_u64 v[222:223], s[62:63], 0, v[138:139]
	global_load_lds_dwordx4 v[222:223], off
	s_add_i32 m0, s79, 0x2000
	v_lshl_add_u64 v[224:225], s[62:63], 0, v[142:143]
	global_load_lds_dwordx4 v[224:225], off
	s_mov_b32 m0, s35
	v_lshl_add_u64 v[226:227], s[64:65], 0, v[136:137]
	global_load_lds_dwordx4 v[226:227], off
	s_mov_b32 m0, s66
	v_lshl_add_u64 v[228:229], s[64:65], 0, v[140:141]
	global_load_lds_dwordx4 v[228:229], off
	s_add_u32 s80, s62, 0x40000
	s_addc_u32 s81, s63, 0
	s_add_i32 s79, s76, s33
	s_mov_b32 m0, s79
	v_lshl_add_u64 v[240:241], s[80:81], 0, v[138:139]
	global_load_lds_dwordx4 v[240:241], off
	s_add_i32 m0, s79, 0x2000
	v_lshl_add_u64 v[240:241], s[80:81], 0, v[142:143]
	global_load_lds_dwordx4 v[240:241], off
	s_waitcnt vmcnt(8) lgkmcnt(0)
	s_barrier
; #define PG8_STAGE(bufoff, gbase, voff) do { _Pragma("unroll") for (int _i = 0; _i < 2; ++_i) \
;         __builtin_amdgcn_global_load_lds((const unsigned*)((const char*)(gbase) + (voff)[_i]), (LAS unsigned*)(lds + (bufoff) + ldsw + _i * 8192), 16, 0, 0); } while (0)
; #define PG8_LDA(dst, b, h) do { _Pragma("unroll") for (int m = 0; m < 4; ++m) _Pragma("unroll") for (int k = 0; k < 2; ++k) dst[m][k] = *(const LAS bf16x8*)(lds + PG8_SA(b, h) + aoff + m * 2048 + k * 1024); } while (0)
; #define PG8_LDB(dst, b, h) do { _Pragma("unroll") for (int n = 0; n < 2; ++n) _Pragma("unroll") for (int k = 0; k < 2; ++k) dst[n][k] = *(const LAS bf16x8*)(lds + PG8_SB(b, h) + boff + n * 2048 + k * 1024); } while (0)
; #define PG8_MMA(ai, bj, At, Bt) do { __builtin_amdgcn_s_setprio(1); _Pragma("unroll") for (int m = 0; m < 4; ++m) _Pragma("unroll") for (int n = 0; n < 2; ++n) _Pragma("unroll") for (int k = 0; k < 2; ++k) \
;         acc[ai][bj][m][n] = __builtin_amdgcn_mfma_f32_16x16x32_bf16(Bt[n][k], At[m][k], acc[ai][bj][m][n], 0, 0, 0); __builtin_amdgcn_s_setprio(0); } while (0)
; #define PG8_WAIT_V(n) asm volatile("s_waitcnt vmcnt(" #n ")" ::: "memory")
; #define PG8_WAIT_L(n) asm volatile("s_waitcnt lgkmcnt(" #n ")" ::: "memory")
; #define PG8_BAR __builtin_amdgcn_s_barrier()
; #define PG8_SCHED __builtin_amdgcn_sched_barrier(0)
; template <class Epi>
; __device__ __forceinline__ void gemm_phase(LAS unsigned char* lds, const Gemm g, const StaticOrder& S, const Epi& E) {
;     ...
;             PG8_BAR; PG8_WAIT_L(0); PG8_MMA(1, 0, At, B0); PG8_BAR; PG8_SCHED;
;             PG8_STAGE(PG8_SB(0, 1), b2 + hstepB, voffB);
;             PG8_WAIT_V(6); PG8_BAR; PG8_MMA(1, 1, At, B1); PG8_BAR;
;             PG8_LDB(B0, 1, 0); PG8_SCHED; PG8_LDA(At, 1, 0); PG8_STAGE(PG8_SA(0, 1), a2 + hstepA, voffA);
;             PG8_WAIT_L(8); PG8_BAR; PG8_WAIT_L(0); PG8_MMA(0, 0, At, B0); PG8_BAR; PG8_SCHED;
;             PG8_LDB(B1, 1, 1); PG8_STAGE(PG8_SB(1, 0), b3, voffB);
;             PG8_BAR; PG8_WAIT_L(0); PG8_MMA(0, 1, At, B1); PG8_BAR;
	v_mfma_f32_16x16x32_bf16 v[60:63], v[152:155], v[174:177], 0
	v_mfma_f32_16x16x32_bf16 v[56:59], v[166:169], v[174:177], 0
	v_mfma_f32_16x16x32_bf16 v[52:55], v[152:155], v[182:185], 0
	v_mfma_f32_16x16x32_bf16 v[44:47], v[166:169], v[182:185], 0
	v_mfma_f32_16x16x32_bf16 v[36:39], v[152:155], v[190:193], 0
	v_mfma_f32_16x16x32_bf16 v[28:31], v[166:169], v[190:193], 0
	v_mfma_f32_16x16x32_bf16 v[20:23], v[152:155], v[198:201], 0
	v_mfma_f32_16x16x32_bf16 v[12:15], v[166:169], v[198:201], 0
	v_mfma_f32_16x16x32_bf16 v[60:63], v[162:165], v[178:181], v[60:63]
	v_mfma_f32_16x16x32_bf16 v[56:59], v[170:173], v[178:181], v[56:59]
	v_mfma_f32_16x16x32_bf16 v[52:55], v[162:165], v[186:189], v[52:55]
	v_mfma_f32_16x16x32_bf16 v[44:47], v[170:173], v[186:189], v[44:47]
	v_mfma_f32_16x16x32_bf16 v[36:39], v[162:165], v[194:197], v[36:39]
	v_mfma_f32_16x16x32_bf16 v[28:31], v[170:173], v[194:197], v[28:31]
	v_mfma_f32_16x16x32_bf16 v[20:23], v[162:165], v[202:205], v[20:23]
	v_mfma_f32_16x16x32_bf16 v[12:15], v[170:173], v[202:205], v[12:15]
	v_mfma_f32_16x16x32_bf16 v[48:51], v[206:209], v[174:177], 0
	v_mfma_f32_16x16x32_bf16 v[40:43], v[214:217], v[174:177], 0
	v_mfma_f32_16x16x32_bf16 v[32:35], v[206:209], v[182:185], 0
	v_mfma_f32_16x16x32_bf16 v[24:27], v[214:217], v[182:185], 0
	v_mfma_f32_16x16x32_bf16 v[16:19], v[206:209], v[190:193], 0
	v_mfma_f32_16x16x32_bf16 v[8:11], v[214:217], v[190:193], 0
	v_mfma_f32_16x16x32_bf16 v[4:7], v[206:209], v[198:201], 0
	v_mfma_f32_16x16x32_bf16 v[0:3], v[214:217], v[198:201], 0
	v_mfma_f32_16x16x32_bf16 v[48:51], v[210:213], v[178:181], v[48:51]
	v_mfma_f32_16x16x32_bf16 v[40:43], v[218:221], v[178:181], v[40:43]
	v_mfma_f32_16x16x32_bf16 v[32:35], v[210:213], v[186:189], v[32:35]
	v_mfma_f32_16x16x32_bf16 v[24:27], v[218:221], v[186:189], v[24:27]
	v_mfma_f32_16x16x32_bf16 v[16:19], v[210:213], v[194:197], v[16:19]
	v_mfma_f32_16x16x32_bf16 v[8:11], v[218:221], v[194:197], v[8:11]
	v_mfma_f32_16x16x32_bf16 v[4:7], v[210:213], v[202:205], v[4:7]
	v_mfma_f32_16x16x32_bf16 v[0:3], v[218:221], v[202:205], v[0:3]
	s_barrier
	s_add_i32 s79, 0, 0x18000
	v_add_u32_e32 v170, s79, v156
	ds_read_b128 v[152:155], v170
	ds_read_b128 v[162:165], v170 offset:1024
	ds_read_b128 v[166:169], v170 offset:2048
	ds_read_b128 v[170:173], v170 offset:3072
	ds_read_b128 v[174:177], v160 offset:32768
	ds_read_b128 v[178:181], v160 offset:33792
	ds_read_b128 v[182:185], v160 offset:34816
	ds_read_b128 v[186:189], v160 offset:35840
	ds_read_b128 v[190:193], v160 offset:36864
	ds_read_b128 v[194:197], v160 offset:37888
	ds_read_b128 v[198:201], v160 offset:38912
	ds_read_b128 v[202:205], v160 offset:39936
	s_add_i32 s98, 0, 0x1c000
	v_add_u32_e32 v218, s98, v156
	ds_read_b128 v[206:209], v218
	ds_read_b128 v[210:213], v218 offset:1024
	ds_read_b128 v[214:217], v218 offset:2048
	ds_read_b128 v[218:221], v218 offset:3072
	s_add_u32 s64, s64, 0x40000
	s_addc_u32 s65, s65, 0
	s_mov_b32 m0, s67
	v_lshl_add_u64 v[244:245], s[64:65], 0, v[136:137]
	global_load_lds_dwordx4 v[244:245], off
	s_mov_b32 m0, s68
	v_lshl_add_u64 v[244:245], s[64:65], 0, v[140:141]
	global_load_lds_dwordx4 v[244:245], off
	s_waitcnt vmcnt(8) lgkmcnt(0)
	s_barrier
	v_mfma_f32_16x16x32_bf16 v[124:127], v[152:155], v[174:177], v[124:127]
	v_mfma_f32_16x16x32_bf16 v[120:123], v[166:169], v[174:177], v[120:123]
	v_mfma_f32_16x16x32_bf16 v[116:119], v[152:155], v[182:185], v[116:119]
	v_mfma_f32_16x16x32_bf16 v[108:111], v[166:169], v[182:185], v[108:111]
	v_mfma_f32_16x16x32_bf16 v[100:103], v[152:155], v[190:193], v[100:103]
	v_mfma_f32_16x16x32_bf16 v[92:95], v[166:169], v[190:193], v[92:95]
	v_mfma_f32_16x16x32_bf16 v[84:87], v[152:155], v[198:201], v[84:87]
	v_mfma_f32_16x16x32_bf16 v[76:79], v[166:169], v[198:201], v[76:79]
	v_mfma_f32_16x16x32_bf16 v[124:127], v[162:165], v[178:181], v[124:127]
	v_mfma_f32_16x16x32_bf16 v[120:123], v[170:173], v[178:181], v[120:123]
	v_mfma_f32_16x16x32_bf16 v[116:119], v[162:165], v[186:189], v[116:119]
	v_mfma_f32_16x16x32_bf16 v[108:111], v[170:173], v[186:189], v[108:111]
	v_mfma_f32_16x16x32_bf16 v[100:103], v[162:165], v[194:197], v[100:103]
	v_mfma_f32_16x16x32_bf16 v[92:95], v[170:173], v[194:197], v[92:95]
	v_mfma_f32_16x16x32_bf16 v[84:87], v[162:165], v[202:205], v[84:87]
	v_mfma_f32_16x16x32_bf16 v[76:79], v[170:173], v[202:205], v[76:79]
	v_mfma_f32_16x16x32_bf16 v[112:115], v[206:209], v[174:177], v[112:115]
	v_mfma_f32_16x16x32_bf16 v[104:107], v[214:217], v[174:177], v[104:107]
	v_mfma_f32_16x16x32_bf16 v[96:99], v[206:209], v[182:185], v[96:99]
	v_mfma_f32_16x16x32_bf16 v[88:91], v[214:217], v[182:185], v[88:91]
	v_mfma_f32_16x16x32_bf16 v[80:83], v[206:209], v[190:193], v[80:83]
	v_mfma_f32_16x16x32_bf16 v[72:75], v[214:217], v[190:193], v[72:75]
	v_mfma_f32_16x16x32_bf16 v[68:71], v[206:209], v[198:201], v[68:71]
	v_mfma_f32_16x16x32_bf16 v[64:67], v[214:217], v[198:201], v[64:67]
	v_mfma_f32_16x16x32_bf16 v[112:115], v[210:213], v[178:181], v[112:115]
	v_mfma_f32_16x16x32_bf16 v[104:107], v[218:221], v[178:181], v[104:107]
	v_mfma_f32_16x16x32_bf16 v[96:99], v[210:213], v[186:189], v[96:99]
	v_mfma_f32_16x16x32_bf16 v[88:91], v[218:221], v[186:189], v[88:91]
	v_mfma_f32_16x16x32_bf16 v[80:83], v[210:213], v[194:197], v[80:83]
	v_mfma_f32_16x16x32_bf16 v[72:75], v[218:221], v[194:197], v[72:75]
	v_mfma_f32_16x16x32_bf16 v[68:71], v[210:213], v[202:205], v[68:71]
	v_mfma_f32_16x16x32_bf16 v[64:67], v[218:221], v[202:205], v[64:67]
	s_barrier
; #define PG8_STAGE(bufoff, gbase, voff) do { _Pragma("unroll") for (int _i = 0; _i < 2; ++_i) \
;         __builtin_amdgcn_global_load_lds((const unsigned*)((const char*)(gbase) + (voff)[_i]), (LAS unsigned*)(lds + (bufoff) + ldsw + _i * 8192), 16, 0, 0); } while (0)
; #define PG8_LDA(dst, b, h) do { _Pragma("unroll") for (int m = 0; m < 4; ++m) _Pragma("unroll") for (int k = 0; k < 2; ++k) dst[m][k] = *(const LAS bf16x8*)(lds + PG8_SA(b, h) + aoff + m * 2048 + k * 1024); } while (0)
; #define PG8_MMA(ai, bj, At, Bt) do { __builtin_amdgcn_s_setprio(1); _Pragma("unroll") for (int m = 0; m < 4; ++m) _Pragma("unroll") for (int n = 0; n < 2; ++n) _Pragma("unroll") for (int k = 0; k < 2; ++k) \
;         acc[ai][bj][m][n] = __builtin_amdgcn_mfma_f32_16x16x32_bf16(Bt[n][k], At[m][k], acc[ai][bj][m][n], 0, 0, 0); __builtin_amdgcn_s_setprio(0); } while (0)
; #define PG8_WAIT_V(n) asm volatile("s_waitcnt vmcnt(" #n ")" ::: "memory")
; #define PG8_WAIT_L(n) asm volatile("s_waitcnt lgkmcnt(" #n ")" ::: "memory")
; #define PG8_BAR __builtin_amdgcn_s_barrier()
; #define PG8_SCHED __builtin_amdgcn_sched_barrier(0)
; template <class Epi>
; __device__ __forceinline__ void gemm_phase(LAS unsigned char* lds, const Gemm g, const StaticOrder& S, const Epi& E) {
;     ...
;             PG8_LDA(At, 1, 1); PG8_STAGE(PG8_SA(1, 0), a3, voffA);
;             PG8_BAR; PG8_WAIT_L(0); PG8_MMA(1, 0, At, B0); PG8_BAR; PG8_SCHED;
;             PG8_STAGE(PG8_SB(1, 1), b3 + hstepB, voffB);
;             PG8_WAIT_V(6); PG8_BAR; PG8_MMA(1, 1, At, B1); PG8_BAR;
	ds_read_b128 v[174:177], v160 offset:49152
	ds_read_b128 v[178:181], v160 offset:50176
	ds_read_b128 v[182:185], v160 offset:51200
	ds_read_b128 v[186:189], v160 offset:52224
	ds_read_b128 v[190:193], v160 offset:53248
	ds_read_b128 v[194:197], v160 offset:54272
	ds_read_b128 v[198:201], v160 offset:55296
	ds_read_b128 v[202:205], v160 offset:56320
	s_add_i32 s65, s79, s33
	s_mov_b32 m0, s65
	v_lshl_add_u64 v[222:223], v[222:223], 0, s[28:29]
	global_load_lds_dwordx4 v[222:223], off
	s_add_i32 m0, s65, 0x2000
	v_lshl_add_u64 v[222:223], v[224:225], 0, s[28:29]
	global_load_lds_dwordx4 v[222:223], off
	s_mov_b32 m0, s71
	v_lshl_add_u64 v[222:223], v[226:227], 0, s[28:29]
	global_load_lds_dwordx4 v[222:223], off
	s_mov_b32 m0, s72
	v_lshl_add_u64 v[222:223], v[228:229], 0, s[28:29]
	global_load_lds_dwordx4 v[222:223], off
	s_add_u32 s62, s62, 0x40080
	s_addc_u32 s63, s63, 0
	s_add_i32 s64, s98, s33
	s_mov_b32 m0, s64
	v_lshl_add_u64 v[240:241], s[62:63], 0, v[138:139]
	global_load_lds_dwordx4 v[240:241], off
	s_add_i32 m0, s64, 0x2000
	v_lshl_add_u64 v[240:241], s[62:63], 0, v[142:143]
	global_load_lds_dwordx4 v[240:241], off
	s_waitcnt vmcnt(8) lgkmcnt(0)
	s_barrier
	v_mfma_f32_16x16x32_bf16 v[60:63], v[152:155], v[174:177], v[60:63]
	v_mfma_f32_16x16x32_bf16 v[56:59], v[166:169], v[174:177], v[56:59]
	v_mfma_f32_16x16x32_bf16 v[52:55], v[152:155], v[182:185], v[52:55]
	v_mfma_f32_16x16x32_bf16 v[44:47], v[166:169], v[182:185], v[44:47]
	v_mfma_f32_16x16x32_bf16 v[36:39], v[152:155], v[190:193], v[36:39]
	v_mfma_f32_16x16x32_bf16 v[28:31], v[166:169], v[190:193], v[28:31]
	v_mfma_f32_16x16x32_bf16 v[20:23], v[152:155], v[198:201], v[20:23]
	v_mfma_f32_16x16x32_bf16 v[12:15], v[166:169], v[198:201], v[12:15]
	v_mfma_f32_16x16x32_bf16 v[60:63], v[162:165], v[178:181], v[60:63]
	v_mfma_f32_16x16x32_bf16 v[56:59], v[170:173], v[178:181], v[56:59]
	v_mfma_f32_16x16x32_bf16 v[52:55], v[162:165], v[186:189], v[52:55]
	v_mfma_f32_16x16x32_bf16 v[44:47], v[170:173], v[186:189], v[44:47]
	v_mfma_f32_16x16x32_bf16 v[36:39], v[162:165], v[194:197], v[36:39]
	v_mfma_f32_16x16x32_bf16 v[28:31], v[170:173], v[194:197], v[28:31]
	v_mfma_f32_16x16x32_bf16 v[20:23], v[162:165], v[202:205], v[20:23]
	v_mfma_f32_16x16x32_bf16 v[12:15], v[170:173], v[202:205], v[12:15]
	v_mfma_f32_16x16x32_bf16 v[48:51], v[206:209], v[174:177], v[48:51]
	v_mfma_f32_16x16x32_bf16 v[40:43], v[214:217], v[174:177], v[40:43]
	v_mfma_f32_16x16x32_bf16 v[32:35], v[206:209], v[182:185], v[32:35]
	v_mfma_f32_16x16x32_bf16 v[24:27], v[214:217], v[182:185], v[24:27]
	v_mfma_f32_16x16x32_bf16 v[16:19], v[206:209], v[190:193], v[16:19]
	v_mfma_f32_16x16x32_bf16 v[8:11], v[214:217], v[190:193], v[8:11]
	v_mfma_f32_16x16x32_bf16 v[4:7], v[206:209], v[198:201], v[4:7]
	v_mfma_f32_16x16x32_bf16 v[0:3], v[214:217], v[198:201], v[0:3]
	v_mfma_f32_16x16x32_bf16 v[48:51], v[210:213], v[178:181], v[48:51]
	v_mfma_f32_16x16x32_bf16 v[40:43], v[218:221], v[178:181], v[40:43]
	v_mfma_f32_16x16x32_bf16 v[32:35], v[210:213], v[186:189], v[32:35]
	v_mfma_f32_16x16x32_bf16 v[24:27], v[218:221], v[186:189], v[24:27]
	v_mfma_f32_16x16x32_bf16 v[16:19], v[210:213], v[194:197], v[16:19]
	v_mfma_f32_16x16x32_bf16 v[8:11], v[218:221], v[194:197], v[8:11]
	v_mfma_f32_16x16x32_bf16 v[4:7], v[210:213], v[202:205], v[4:7]
	v_mfma_f32_16x16x32_bf16 v[0:3], v[218:221], v[202:205], v[0:3]
	s_add_i32 s78, s78, 2
	s_add_u32 s60, s60, 0x100
	s_addc_u32 s61, s61, 0
	s_add_u32 s37, s37, 0x100
	s_addc_u32 s39, s39, 0
	s_cmp_gt_u32 s78, 13
	s_barrier

; #define PG8_STAGE(bufoff, gbase, voff) do { _Pragma("unroll") for (int _i = 0; _i < 2; ++_i) \
;         __builtin_amdgcn_global_load_lds((const unsigned*)((const char*)(gbase) + (voff)[_i]), (LAS unsigned*)(lds + (bufoff) + ldsw + _i * 8192), 16, 0, 0); } while (0)
; #define PG8_LDA(dst, b, h) do { _Pragma("unroll") for (int m = 0; m < 4; ++m) _Pragma("unroll") for (int k = 0; k < 2; ++k) dst[m][k] = *(const LAS bf16x8*)(lds + PG8_SA(b, h) + aoff + m * 2048 + k * 1024); } while (0)
; #define PG8_LDB(dst, b, h) do { _Pragma("unroll") for (int n = 0; n < 2; ++n) _Pragma("unroll") for (int k = 0; k < 2; ++k) dst[n][k] = *(const LAS bf16x8*)(lds + PG8_SB(b, h) + boff + n * 2048 + k * 1024); } while (0)
; #define PG8_MMA(ai, bj, At, Bt) do { __builtin_amdgcn_s_setprio(1); _Pragma("unroll") for (int m = 0; m < 4; ++m) _Pragma("unroll") for (int n = 0; n < 2; ++n) _Pragma("unroll") for (int k = 0; k < 2; ++k) \
;         acc[ai][bj][m][n] = __builtin_amdgcn_mfma_f32_16x16x32_bf16(Bt[n][k], At[m][k], acc[ai][bj][m][n], 0, 0, 0); __builtin_amdgcn_s_setprio(0); } while (0)
; #define PG8_BAR __builtin_amdgcn_s_barrier()
; template <class Epi>
; __device__ __forceinline__ void gemm_phase(LAS unsigned char* lds, const Gemm g, const StaticOrder& S, const Epi& E) {
;     ...
;         const char* nA = has_next ? (const char*)g.A + (size_t)nxt.pm * tstepA + (size_t)nxt.kt0 * kstep : cA; const char* nB = has_next ? (const char*)g.Bt + (size_t)nxt.pn * tstepB + (size_t)nxt.kt0 * kstep : cB;
;         const int nt = cur.nkt;
;         for (int t = 0; t < nt; t += 2) {
;             const bool last = (t == nt - 2);
;             const char* a1 = cA + (size_t)(t + 1) * kstep;
;             const char* a2 = last ? nA : cA + (size_t)(t + 2) * kstep; const char* b2 = last ? nB : cB + (size_t)(t + 2) * kstep;
;             const char* a3 = a2 + kstep; const char* b3 = b2 + kstep;
;             PG8_LDB(B0, 0, 0); PG8_SCHED; PG8_LDA(At, 0, 0); PG8_STAGE(PG8_SA(1, 1), a1 + hstepA, voffA);
;             PG8_WAIT_L(8); PG8_BAR; PG8_WAIT_L(0); PG8_MMA(0, 0, At, B0); PG8_BAR; PG8_SCHED;
;             PG8_LDB(B1, 0, 1); PG8_STAGE(PG8_SB(0, 0), b2, voffB);
;             PG8_BAR; PG8_WAIT_L(0); PG8_MMA(0, 1, At, B1); PG8_BAR;
;             PG8_LDA(At, 0, 1); PG8_STAGE(PG8_SA(0, 0), a2, voffA);
;             PG8_BAR; PG8_WAIT_L(0); PG8_MMA(1, 0, At, B0); PG8_BAR; PG8_SCHED;
.LBB0_909:
	s_add_i32 s18, s81, -2
	s_add_u32 s46, s46, 0x160080
	s_addc_u32 s47, s47, 0
	s_add_u32 s41, s54, 0x100
	s_addc_u32 s82, s55, 0
	s_mov_b32 s54, 0
	s_add_i32 s83, s54, 2
	s_add_u32 s55, s46, 0xffea0080
	s_addc_u32 s56, s47, -1
	s_cmp_eq_u32 s18, s54
	s_cselect_b32 s54, s0, s41
	s_cselect_b32 s57, s45, s56
	s_cselect_b32 s56, s44, s55
	s_cselect_b32 s55, s1, s82
	ds_read_b128 v[150:153], v170
	ds_read_b128 v[154:157], v170 offset:1024
	ds_read_b128 v[174:177], v170 offset:2048
	ds_read_b128 v[178:181], v170 offset:3072
	ds_read_b128 v[182:185], v171
	ds_read_b128 v[186:189], v171 offset:1024
	ds_read_b128 v[190:193], v171 offset:2048
	ds_read_b128 v[194:197], v171 offset:3072
	ds_read_b128 v[198:201], v171 offset:4096
	ds_read_b128 v[202:205], v171 offset:5120
	ds_read_b128 v[206:209], v171 offset:6144
	ds_read_b128 v[210:213], v171 offset:7168
	ds_read_b128 v[214:217], v172
	ds_read_b128 v[218:221], v172 offset:1024
	ds_read_b128 v[222:225], v172 offset:2048
	ds_read_b128 v[226:229], v172 offset:3072
	s_add_i32 m0, s33, 0xc000
	v_lshl_add_u64 v[158:159], s[46:47], 0, v[144:145]
	global_load_lds_dwordx4 v[158:159], off
	s_add_i32 m0, s33, 0xe000
	v_lshl_add_u64 v[158:159], s[46:47], 0, v[146:147]
	global_load_lds_dwordx4 v[158:159], off
	s_waitcnt vmcnt(8) lgkmcnt(0)
	s_barrier
	v_mfma_f32_16x16x32_bf16 v[124:127], v[150:153], v[182:185], 0
	v_mfma_f32_16x16x32_bf16 v[120:123], v[174:177], v[182:185], 0
	v_mfma_f32_16x16x32_bf16 v[116:119], v[150:153], v[190:193], 0
	v_mfma_f32_16x16x32_bf16 v[108:111], v[174:177], v[190:193], 0
	v_mfma_f32_16x16x32_bf16 v[100:103], v[150:153], v[198:201], 0
	v_mfma_f32_16x16x32_bf16 v[92:95], v[174:177], v[198:201], 0
	v_mfma_f32_16x16x32_bf16 v[84:87], v[150:153], v[206:209], 0
	v_mfma_f32_16x16x32_bf16 v[76:79], v[174:177], v[206:209], 0
	v_mfma_f32_16x16x32_bf16 v[124:127], v[154:157], v[186:189], v[124:127]
	v_mfma_f32_16x16x32_bf16 v[120:123], v[178:181], v[186:189], v[120:123]
	v_mfma_f32_16x16x32_bf16 v[116:119], v[154:157], v[194:197], v[116:119]
	v_mfma_f32_16x16x32_bf16 v[108:111], v[178:181], v[194:197], v[108:111]
	v_mfma_f32_16x16x32_bf16 v[100:103], v[154:157], v[202:205], v[100:103]
	v_mfma_f32_16x16x32_bf16 v[92:95], v[178:181], v[202:205], v[92:95]
	v_mfma_f32_16x16x32_bf16 v[84:87], v[154:157], v[210:213], v[84:87]
	v_mfma_f32_16x16x32_bf16 v[76:79], v[178:181], v[210:213], v[76:79]
	v_mfma_f32_16x16x32_bf16 v[112:115], v[214:217], v[182:185], 0
	v_mfma_f32_16x16x32_bf16 v[104:107], v[222:225], v[182:185], 0
	v_mfma_f32_16x16x32_bf16 v[96:99], v[214:217], v[190:193], 0
	v_mfma_f32_16x16x32_bf16 v[88:91], v[222:225], v[190:193], 0
	v_mfma_f32_16x16x32_bf16 v[80:83], v[214:217], v[198:201], 0
	v_mfma_f32_16x16x32_bf16 v[72:75], v[222:225], v[198:201], 0
	v_mfma_f32_16x16x32_bf16 v[68:71], v[214:217], v[206:209], 0
	v_mfma_f32_16x16x32_bf16 v[64:67], v[222:225], v[206:209], 0
	v_mfma_f32_16x16x32_bf16 v[112:115], v[218:221], v[186:189], v[112:115]
	v_mfma_f32_16x16x32_bf16 v[104:107], v[226:229], v[186:189], v[104:107]
	v_mfma_f32_16x16x32_bf16 v[96:99], v[218:221], v[194:197], v[96:99]
	v_mfma_f32_16x16x32_bf16 v[88:91], v[226:229], v[194:197], v[88:91]
	v_mfma_f32_16x16x32_bf16 v[80:83], v[218:221], v[202:205], v[80:83]
	v_mfma_f32_16x16x32_bf16 v[72:75], v[226:229], v[202:205], v[72:75]
	v_mfma_f32_16x16x32_bf16 v[68:71], v[218:221], v[210:213], v[68:71]
	v_mfma_f32_16x16x32_bf16 v[64:67], v[226:229], v[210:213], v[64:67]
	s_barrier
	ds_read_b128 v[182:185], v171 offset:16384
	ds_read_b128 v[186:189], v171 offset:17408
	ds_read_b128 v[190:193], v171 offset:18432
	ds_read_b128 v[194:197], v171 offset:19456
	ds_read_b128 v[198:201], v171 offset:20480
	ds_read_b128 v[202:205], v171 offset:21504
	ds_read_b128 v[206:209], v171 offset:22528
	ds_read_b128 v[210:213], v171 offset:23552
	s_add_i32 s84, s65, s21
	s_mov_b32 m0, s84
	v_lshl_add_u64 v[158:159], s[54:55], 0, v[138:139]
	global_load_lds_dwordx4 v[158:159], off
	s_add_i32 m0, s84, 0x2000
	v_lshl_add_u64 v[230:231], s[54:55], 0, v[142:143]
	global_load_lds_dwordx4 v[230:231], off
	s_mov_b32 m0, s33
	v_lshl_add_u64 v[232:233], s[56:57], 0, v[136:137]
	global_load_lds_dwordx4 v[232:233], off
	s_mov_b32 m0, s35
	v_lshl_add_u64 v[234:235], s[56:57], 0, v[140:141]
	global_load_lds_dwordx4 v[234:235], off
	s_add_u32 s84, s54, 0xb0000
	s_addc_u32 s85, s55, 0
	s_add_i32 s86, s66, s21
	s_mov_b32 m0, s86
	v_lshl_add_u64 v[240:241], s[84:85], 0, v[138:139]
	global_load_lds_dwordx4 v[240:241], off
	s_add_i32 m0, s86, 0x2000
	v_lshl_add_u64 v[240:241], s[84:85], 0, v[142:143]
	global_load_lds_dwordx4 v[240:241], off
	s_waitcnt vmcnt(8) lgkmcnt(0)
	s_barrier
; #define PG8_STAGE(bufoff, gbase, voff) do { _Pragma("unroll") for (int _i = 0; _i < 2; ++_i) \
;         __builtin_amdgcn_global_load_lds((const unsigned*)((const char*)(gbase) + (voff)[_i]), (LAS unsigned*)(lds + (bufoff) + ldsw + _i * 8192), 16, 0, 0); } while (0)
; #define PG8_LDA(dst, b, h) do { _Pragma("unroll") for (int m = 0; m < 4; ++m) _Pragma("unroll") for (int k = 0; k < 2; ++k) dst[m][k] = *(const LAS bf16x8*)(lds + PG8_SA(b, h) + aoff + m * 2048 + k * 1024); } while (0)
; #define PG8_LDB(dst, b, h) do { _Pragma("unroll") for (int n = 0; n < 2; ++n) _Pragma("unroll") for (int k = 0; k < 2; ++k) dst[n][k] = *(const LAS bf16x8*)(lds + PG8_SB(b, h) + boff + n * 2048 + k * 1024); } while (0)
; #define PG8_MMA(ai, bj, At, Bt) do { __builtin_amdgcn_s_setprio(1); _Pragma("unroll") for (int m = 0; m < 4; ++m) _Pragma("unroll") for (int n = 0; n < 2; ++n) _Pragma("unroll") for (int k = 0; k < 2; ++k) \
;         acc[ai][bj][m][n] = __builtin_amdgcn_mfma_f32_16x16x32_bf16(Bt[n][k], At[m][k], acc[ai][bj][m][n], 0, 0, 0); __builtin_amdgcn_s_setprio(0); } while (0)
; #define PG8_WAIT_V(n) asm volatile("s_waitcnt vmcnt(" #n ")" ::: "memory")
; #define PG8_WAIT_L(n) asm volatile("s_waitcnt lgkmcnt(" #n ")" ::: "memory")
; #define PG8_BAR __builtin_amdgcn_s_barrier()
; #define PG8_SCHED __builtin_amdgcn_sched_barrier(0)
; template <class Epi>
; __device__ __forceinline__ void gemm_phase(LAS unsigned char* lds, const Gemm g, const StaticOrder& S, const Epi& E) {
;     ...
;             PG8_BAR; PG8_WAIT_L(0); PG8_MMA(1, 0, At, B0); PG8_BAR; PG8_SCHED;
;             PG8_STAGE(PG8_SB(0, 1), b2 + hstepB, voffB);
;             PG8_WAIT_V(6); PG8_BAR; PG8_MMA(1, 1, At, B1); PG8_BAR;
;             PG8_LDB(B0, 1, 0); PG8_SCHED; PG8_LDA(At, 1, 0); PG8_STAGE(PG8_SA(0, 1), a2 + hstepA, voffA);
;             PG8_WAIT_L(8); PG8_BAR; PG8_WAIT_L(0); PG8_MMA(0, 0, At, B0); PG8_BAR; PG8_SCHED;
;             PG8_LDB(B1, 1, 1); PG8_STAGE(PG8_SB(1, 0), b3, voffB);
;             PG8_BAR; PG8_WAIT_L(0); PG8_MMA(0, 1, At, B1); PG8_BAR;
	v_mfma_f32_16x16x32_bf16 v[60:63], v[150:153], v[182:185], 0
	v_mfma_f32_16x16x32_bf16 v[56:59], v[174:177], v[182:185], 0
	v_mfma_f32_16x16x32_bf16 v[52:55], v[150:153], v[190:193], 0
	v_mfma_f32_16x16x32_bf16 v[44:47], v[174:177], v[190:193], 0
	v_mfma_f32_16x16x32_bf16 v[36:39], v[150:153], v[198:201], 0
	v_mfma_f32_16x16x32_bf16 v[28:31], v[174:177], v[198:201], 0
	v_mfma_f32_16x16x32_bf16 v[20:23], v[150:153], v[206:209], 0
	v_mfma_f32_16x16x32_bf16 v[12:15], v[174:177], v[206:209], 0
	v_mfma_f32_16x16x32_bf16 v[60:63], v[154:157], v[186:189], v[60:63]
	v_mfma_f32_16x16x32_bf16 v[56:59], v[178:181], v[186:189], v[56:59]
	v_mfma_f32_16x16x32_bf16 v[52:55], v[154:157], v[194:197], v[52:55]
	v_mfma_f32_16x16x32_bf16 v[44:47], v[178:181], v[194:197], v[44:47]
	v_mfma_f32_16x16x32_bf16 v[36:39], v[154:157], v[202:205], v[36:39]
	v_mfma_f32_16x16x32_bf16 v[28:31], v[178:181], v[202:205], v[28:31]
	v_mfma_f32_16x16x32_bf16 v[20:23], v[154:157], v[210:213], v[20:23]
	v_mfma_f32_16x16x32_bf16 v[12:15], v[178:181], v[210:213], v[12:15]
	v_mfma_f32_16x16x32_bf16 v[48:51], v[214:217], v[182:185], 0
	v_mfma_f32_16x16x32_bf16 v[40:43], v[222:225], v[182:185], 0
	v_mfma_f32_16x16x32_bf16 v[32:35], v[214:217], v[190:193], 0
	v_mfma_f32_16x16x32_bf16 v[24:27], v[222:225], v[190:193], 0
	v_mfma_f32_16x16x32_bf16 v[16:19], v[214:217], v[198:201], 0
	v_mfma_f32_16x16x32_bf16 v[8:11], v[222:225], v[198:201], 0
	v_mfma_f32_16x16x32_bf16 v[4:7], v[214:217], v[206:209], 0
	v_mfma_f32_16x16x32_bf16 v[0:3], v[222:225], v[206:209], 0
	v_mfma_f32_16x16x32_bf16 v[48:51], v[218:221], v[186:189], v[48:51]
	v_mfma_f32_16x16x32_bf16 v[40:43], v[226:229], v[186:189], v[40:43]
	v_mfma_f32_16x16x32_bf16 v[32:35], v[218:221], v[194:197], v[32:35]
	v_mfma_f32_16x16x32_bf16 v[24:27], v[226:229], v[194:197], v[24:27]
	v_mfma_f32_16x16x32_bf16 v[16:19], v[218:221], v[202:205], v[16:19]
	v_mfma_f32_16x16x32_bf16 v[8:11], v[226:229], v[202:205], v[8:11]
	v_mfma_f32_16x16x32_bf16 v[4:7], v[218:221], v[210:213], v[4:7]
	v_mfma_f32_16x16x32_bf16 v[0:3], v[226:229], v[210:213], v[0:3]
	s_barrier
	s_add_i32 s84, 0, 0x18000
	v_add_u32_e32 v173, s84, v168
	ds_read_b128 v[150:153], v173
	ds_read_b128 v[154:157], v173 offset:1024
	ds_read_b128 v[174:177], v173 offset:2048
	ds_read_b128 v[178:181], v173 offset:3072
	ds_read_b128 v[182:185], v171 offset:32768
	ds_read_b128 v[186:189], v171 offset:33792
	ds_read_b128 v[190:193], v171 offset:34816
	ds_read_b128 v[194:197], v171 offset:35840
	ds_read_b128 v[198:201], v171 offset:36864
	ds_read_b128 v[202:205], v171 offset:37888
	ds_read_b128 v[206:209], v171 offset:38912
	ds_read_b128 v[210:213], v171 offset:39936
	s_add_i32 s98, 0, 0x1c000
	v_add_u32_e32 v246, s98, v168
	ds_read_b128 v[214:217], v246
	ds_read_b128 v[218:221], v246 offset:1024
	ds_read_b128 v[222:225], v246 offset:2048
	ds_read_b128 v[226:229], v246 offset:3072
	s_add_u32 s56, s56, 0x160000
	s_addc_u32 s57, s57, 0
	s_mov_b32 m0, s58
	v_lshl_add_u64 v[244:245], s[56:57], 0, v[136:137]
	global_load_lds_dwordx4 v[244:245], off
	s_mov_b32 m0, s59
	v_lshl_add_u64 v[244:245], s[56:57], 0, v[140:141]
	global_load_lds_dwordx4 v[244:245], off
	s_waitcnt vmcnt(8) lgkmcnt(0)
	s_barrier
	v_mfma_f32_16x16x32_bf16 v[124:127], v[150:153], v[182:185], v[124:127]
	v_mfma_f32_16x16x32_bf16 v[120:123], v[174:177], v[182:185], v[120:123]
	v_mfma_f32_16x16x32_bf16 v[116:119], v[150:153], v[190:193], v[116:119]
	v_mfma_f32_16x16x32_bf16 v[108:111], v[174:177], v[190:193], v[108:111]
	v_mfma_f32_16x16x32_bf16 v[100:103], v[150:153], v[198:201], v[100:103]
	v_mfma_f32_16x16x32_bf16 v[92:95], v[174:177], v[198:201], v[92:95]
	v_mfma_f32_16x16x32_bf16 v[84:87], v[150:153], v[206:209], v[84:87]
	v_mfma_f32_16x16x32_bf16 v[76:79], v[174:177], v[206:209], v[76:79]
	v_mfma_f32_16x16x32_bf16 v[124:127], v[154:157], v[186:189], v[124:127]
	v_mfma_f32_16x16x32_bf16 v[120:123], v[178:181], v[186:189], v[120:123]
	v_mfma_f32_16x16x32_bf16 v[116:119], v[154:157], v[194:197], v[116:119]
	v_mfma_f32_16x16x32_bf16 v[108:111], v[178:181], v[194:197], v[108:111]
	v_mfma_f32_16x16x32_bf16 v[100:103], v[154:157], v[202:205], v[100:103]
	v_mfma_f32_16x16x32_bf16 v[92:95], v[178:181], v[202:205], v[92:95]
	v_mfma_f32_16x16x32_bf16 v[84:87], v[154:157], v[210:213], v[84:87]
	v_mfma_f32_16x16x32_bf16 v[76:79], v[178:181], v[210:213], v[76:79]
	v_mfma_f32_16x16x32_bf16 v[112:115], v[214:217], v[182:185], v[112:115]
	v_mfma_f32_16x16x32_bf16 v[104:107], v[222:225], v[182:185], v[104:107]
	v_mfma_f32_16x16x32_bf16 v[96:99], v[214:217], v[190:193], v[96:99]
	v_mfma_f32_16x16x32_bf16 v[88:91], v[222:225], v[190:193], v[88:91]
	v_mfma_f32_16x16x32_bf16 v[80:83], v[214:217], v[198:201], v[80:83]
	v_mfma_f32_16x16x32_bf16 v[72:75], v[222:225], v[198:201], v[72:75]
	v_mfma_f32_16x16x32_bf16 v[68:71], v[214:217], v[206:209], v[68:71]
	v_mfma_f32_16x16x32_bf16 v[64:67], v[222:225], v[206:209], v[64:67]
	v_mfma_f32_16x16x32_bf16 v[112:115], v[218:221], v[186:189], v[112:115]
	v_mfma_f32_16x16x32_bf16 v[104:107], v[226:229], v[186:189], v[104:107]
	v_mfma_f32_16x16x32_bf16 v[96:99], v[218:221], v[194:197], v[96:99]
	v_mfma_f32_16x16x32_bf16 v[88:91], v[226:229], v[194:197], v[88:91]
	v_mfma_f32_16x16x32_bf16 v[80:83], v[218:221], v[202:205], v[80:83]
	v_mfma_f32_16x16x32_bf16 v[72:75], v[226:229], v[202:205], v[72:75]
	v_mfma_f32_16x16x32_bf16 v[68:71], v[218:221], v[210:213], v[68:71]
	v_mfma_f32_16x16x32_bf16 v[64:67], v[226:229], v[210:213], v[64:67]
	s_barrier
; #define PG8_STAGE(bufoff, gbase, voff) do { _Pragma("unroll") for (int _i = 0; _i < 2; ++_i) \
;         __builtin_amdgcn_global_load_lds((const unsigned*)((const char*)(gbase) + (voff)[_i]), (LAS unsigned*)(lds + (bufoff) + ldsw + _i * 8192), 16, 0, 0); } while (0)
; #define PG8_LDA(dst, b, h) do { _Pragma("unroll") for (int m = 0; m < 4; ++m) _Pragma("unroll") for (int k = 0; k < 2; ++k) dst[m][k] = *(const LAS bf16x8*)(lds + PG8_SA(b, h) + aoff + m * 2048 + k * 1024); } while (0)
; #define PG8_MMA(ai, bj, At, Bt) do { __builtin_amdgcn_s_setprio(1); _Pragma("unroll") for (int m = 0; m < 4; ++m) _Pragma("unroll") for (int n = 0; n < 2; ++n) _Pragma("unroll") for (int k = 0; k < 2; ++k) \
;         acc[ai][bj][m][n] = __builtin_amdgcn_mfma_f32_16x16x32_bf16(Bt[n][k], At[m][k], acc[ai][bj][m][n], 0, 0, 0); __builtin_amdgcn_s_setprio(0); } while (0)
; #define PG8_WAIT_V(n) asm volatile("s_waitcnt vmcnt(" #n ")" ::: "memory")
; #define PG8_WAIT_L(n) asm volatile("s_waitcnt lgkmcnt(" #n ")" ::: "memory")
; #define PG8_BAR __builtin_amdgcn_s_barrier()
; #define PG8_SCHED __builtin_amdgcn_sched_barrier(0)
; template <class Epi>
; __device__ __forceinline__ void gemm_phase(LAS unsigned char* lds, const Gemm g, const StaticOrder& S, const Epi& E) {
;     ...
;             PG8_LDA(At, 1, 1); PG8_STAGE(PG8_SA(1, 0), a3, voffA);
;             PG8_BAR; PG8_WAIT_L(0); PG8_MMA(1, 0, At, B0); PG8_BAR; PG8_SCHED;
;             PG8_STAGE(PG8_SB(1, 1), b3 + hstepB, voffB);
;             PG8_WAIT_V(6); PG8_BAR; PG8_MMA(1, 1, At, B1); PG8_BAR;
	ds_read_b128 v[182:185], v171 offset:49152
	ds_read_b128 v[186:189], v171 offset:50176
	ds_read_b128 v[190:193], v171 offset:51200
	ds_read_b128 v[194:197], v171 offset:52224
	ds_read_b128 v[198:201], v171 offset:53248
	ds_read_b128 v[202:205], v171 offset:54272
	ds_read_b128 v[206:209], v171 offset:55296
	ds_read_b128 v[210:213], v171 offset:56320
	s_add_i32 s57, s84, s21
	s_mov_b32 m0, s57
	v_lshl_add_u64 v[158:159], v[158:159], 0, s[22:23]
	global_load_lds_dwordx4 v[158:159], off
	s_add_i32 m0, s57, 0x2000
	v_lshl_add_u64 v[158:159], v[230:231], 0, s[22:23]
	global_load_lds_dwordx4 v[158:159], off
	s_mov_b32 m0, s60
	v_lshl_add_u64 v[158:159], v[232:233], 0, s[22:23]
	global_load_lds_dwordx4 v[158:159], off
	s_mov_b32 m0, s61
	v_lshl_add_u64 v[158:159], v[234:235], 0, s[22:23]
	global_load_lds_dwordx4 v[158:159], off
	s_add_u32 s54, s54, 0xb0080
	s_addc_u32 s55, s55, 0
	s_add_i32 s56, s98, s21
	s_mov_b32 m0, s56
	v_lshl_add_u64 v[240:241], s[54:55], 0, v[138:139]
	global_load_lds_dwordx4 v[240:241], off
	s_add_i32 m0, s56, 0x2000
	v_lshl_add_u64 v[240:241], s[54:55], 0, v[142:143]
	global_load_lds_dwordx4 v[240:241], off
	s_waitcnt vmcnt(8) lgkmcnt(0)
	s_barrier
	v_mfma_f32_16x16x32_bf16 v[60:63], v[150:153], v[182:185], v[60:63]
	v_mfma_f32_16x16x32_bf16 v[56:59], v[174:177], v[182:185], v[56:59]
	v_mfma_f32_16x16x32_bf16 v[52:55], v[150:153], v[190:193], v[52:55]
	v_mfma_f32_16x16x32_bf16 v[44:47], v[174:177], v[190:193], v[44:47]
	v_mfma_f32_16x16x32_bf16 v[36:39], v[150:153], v[198:201], v[36:39]
	v_mfma_f32_16x16x32_bf16 v[28:31], v[174:177], v[198:201], v[28:31]
	v_mfma_f32_16x16x32_bf16 v[20:23], v[150:153], v[206:209], v[20:23]
	v_mfma_f32_16x16x32_bf16 v[12:15], v[174:177], v[206:209], v[12:15]
	v_mfma_f32_16x16x32_bf16 v[60:63], v[154:157], v[186:189], v[60:63]
	v_mfma_f32_16x16x32_bf16 v[56:59], v[178:181], v[186:189], v[56:59]
	v_mfma_f32_16x16x32_bf16 v[52:55], v[154:157], v[194:197], v[52:55]
	v_mfma_f32_16x16x32_bf16 v[44:47], v[178:181], v[194:197], v[44:47]
	v_mfma_f32_16x16x32_bf16 v[36:39], v[154:157], v[202:205], v[36:39]
	v_mfma_f32_16x16x32_bf16 v[28:31], v[178:181], v[202:205], v[28:31]
	v_mfma_f32_16x16x32_bf16 v[20:23], v[154:157], v[210:213], v[20:23]
	v_mfma_f32_16x16x32_bf16 v[12:15], v[178:181], v[210:213], v[12:15]
	v_mfma_f32_16x16x32_bf16 v[48:51], v[214:217], v[182:185], v[48:51]
	v_mfma_f32_16x16x32_bf16 v[40:43], v[222:225], v[182:185], v[40:43]
	v_mfma_f32_16x16x32_bf16 v[32:35], v[214:217], v[190:193], v[32:35]
	v_mfma_f32_16x16x32_bf16 v[24:27], v[222:225], v[190:193], v[24:27]
	v_mfma_f32_16x16x32_bf16 v[16:19], v[214:217], v[198:201], v[16:19]
	v_mfma_f32_16x16x32_bf16 v[8:11], v[222:225], v[198:201], v[8:11]
	v_mfma_f32_16x16x32_bf16 v[4:7], v[214:217], v[206:209], v[4:7]
	v_mfma_f32_16x16x32_bf16 v[0:3], v[222:225], v[206:209], v[0:3]
	v_mfma_f32_16x16x32_bf16 v[48:51], v[218:221], v[186:189], v[48:51]
	v_mfma_f32_16x16x32_bf16 v[40:43], v[226:229], v[186:189], v[40:43]
	v_mfma_f32_16x16x32_bf16 v[32:35], v[218:221], v[194:197], v[32:35]
	v_mfma_f32_16x16x32_bf16 v[24:27], v[226:229], v[194:197], v[24:27]
	v_mfma_f32_16x16x32_bf16 v[16:19], v[218:221], v[202:205], v[16:19]
	v_mfma_f32_16x16x32_bf16 v[8:11], v[226:229], v[202:205], v[8:11]
	v_mfma_f32_16x16x32_bf16 v[4:7], v[218:221], v[210:213], v[4:7]
	v_mfma_f32_16x16x32_bf16 v[0:3], v[226:229], v[210:213], v[0:3]
	s_add_u32 s46, s46, 0x100
	s_addc_u32 s47, s47, 0
	s_add_u32 s41, s41, 0x100
	s_addc_u32 s82, s82, 0
	s_cmp_ge_i32 s83, s81
	s_mov_b32 s54, s83
	s_barrier

; #define PG8_STAGE(bufoff, gbase, voff) do { _Pragma("unroll") for (int _i = 0; _i < 2; ++_i) \
;         __builtin_amdgcn_global_load_lds((const unsigned*)((const char*)(gbase) + (voff)[_i]), (LAS unsigned*)(lds + (bufoff) + ldsw + _i * 8192), 16, 0, 0); } while (0)
; #define PG8_LDA(dst, b, h) do { _Pragma("unroll") for (int m = 0; m < 4; ++m) _Pragma("unroll") for (int k = 0; k < 2; ++k) dst[m][k] = *(const LAS bf16x8*)(lds + PG8_SA(b, h) + aoff + m * 2048 + k * 1024); } while (0)
; #define PG8_LDB(dst, b, h) do { _Pragma("unroll") for (int n = 0; n < 2; ++n) _Pragma("unroll") for (int k = 0; k < 2; ++k) dst[n][k] = *(const LAS bf16x8*)(lds + PG8_SB(b, h) + boff + n * 2048 + k * 1024); } while (0)
; #define PG8_MMA(ai, bj, At, Bt) do { __builtin_amdgcn_s_setprio(1); _Pragma("unroll") for (int m = 0; m < 4; ++m) _Pragma("unroll") for (int n = 0; n < 2; ++n) _Pragma("unroll") for (int k = 0; k < 2; ++k) \
;         acc[ai][bj][m][n] = __builtin_amdgcn_mfma_f32_16x16x32_bf16(Bt[n][k], At[m][k], acc[ai][bj][m][n], 0, 0, 0); __builtin_amdgcn_s_setprio(0); } while (0)
; #define PG8_BAR __builtin_amdgcn_s_barrier()
; template <class Epi>
; __device__ __forceinline__ void gemm_phase(LAS unsigned char* lds, const Gemm g, const StaticOrder& S, const Epi& E) {
;     ...
;         const char* nA = has_next ? (const char*)g.A + (size_t)nxt.pm * tstepA + (size_t)nxt.kt0 * kstep : cA; const char* nB = has_next ? (const char*)g.Bt + (size_t)nxt.pn * tstepB + (size_t)nxt.kt0 * kstep : cB;
;         const int nt = cur.nkt;
;         for (int t = 0; t < nt; t += 2) {
;             const bool last = (t == nt - 2);
;             const char* a1 = cA + (size_t)(t + 1) * kstep;
;             const char* a2 = last ? nA : cA + (size_t)(t + 2) * kstep; const char* b2 = last ? nB : cB + (size_t)(t + 2) * kstep;
;             const char* a3 = a2 + kstep; const char* b3 = b2 + kstep;
;             PG8_LDB(B0, 0, 0); PG8_SCHED; PG8_LDA(At, 0, 0); PG8_STAGE(PG8_SA(1, 1), a1 + hstepA, voffA);
;             PG8_WAIT_L(8); PG8_BAR; PG8_WAIT_L(0); PG8_MMA(0, 0, At, B0); PG8_BAR; PG8_SCHED;
;             PG8_LDB(B1, 0, 1); PG8_STAGE(PG8_SB(0, 0), b2, voffB);
;             PG8_BAR; PG8_WAIT_L(0); PG8_MMA(0, 1, At, B1); PG8_BAR;
;             PG8_LDA(At, 0, 1); PG8_STAGE(PG8_SA(0, 0), a2, voffA);
;             PG8_BAR; PG8_WAIT_L(0); PG8_MMA(1, 0, At, B0); PG8_BAR; PG8_SCHED;
.LBB0_1145:
	s_add_i32 s39, s76, -2
	s_add_u32 s50, s50, 0x40080
	s_addc_u32 s51, s51, 0
	s_add_u32 s41, s54, 0x100
	s_addc_u32 s43, s55, 0
	s_mov_b32 s45, 0
	s_add_i32 s77, s45, 2
	s_add_u32 s54, s50, 0xfffc0080
	s_addc_u32 s55, s51, -1
	s_cmp_eq_u32 s39, s45
	s_cselect_b32 s57, s49, s55
	s_cselect_b32 s56, s48, s54
	s_cselect_b32 s55, s1, s43
	s_cselect_b32 s54, s0, s41
	ds_read_b128 v[150:153], v129
	ds_read_b128 v[154:157], v129 offset:1024
	ds_read_b128 v[158:161], v129 offset:2048
	ds_read_b128 v[166:169], v129 offset:3072
	ds_read_b128 v[170:173], v163
	ds_read_b128 v[174:177], v163 offset:1024
	ds_read_b128 v[178:181], v163 offset:2048
	ds_read_b128 v[182:185], v163 offset:3072
	ds_read_b128 v[186:189], v163 offset:4096
	ds_read_b128 v[190:193], v163 offset:5120
	ds_read_b128 v[194:197], v163 offset:6144
	ds_read_b128 v[198:201], v163 offset:7168
	ds_read_b128 v[202:205], v164
	ds_read_b128 v[206:209], v164 offset:1024
	ds_read_b128 v[210:213], v164 offset:2048
	ds_read_b128 v[214:217], v164 offset:3072
	s_add_i32 m0, s33, 0xc000
	v_lshl_add_u64 v[242:243], s[50:51], 0, v[144:145]
	global_load_lds_dwordx4 v[242:243], off
	s_add_i32 m0, s33, 0xe000
	v_lshl_add_u64 v[242:243], s[50:51], 0, v[146:147]
	global_load_lds_dwordx4 v[242:243], off
	s_waitcnt vmcnt(8) lgkmcnt(0)
	s_barrier
	v_mfma_f32_16x16x32_bf16 v[124:127], v[150:153], v[170:173], 0
	v_mfma_f32_16x16x32_bf16 v[120:123], v[158:161], v[170:173], 0
	v_mfma_f32_16x16x32_bf16 v[116:119], v[150:153], v[178:181], 0
	v_mfma_f32_16x16x32_bf16 v[108:111], v[158:161], v[178:181], 0
	v_mfma_f32_16x16x32_bf16 v[100:103], v[150:153], v[186:189], 0
	v_mfma_f32_16x16x32_bf16 v[92:95], v[158:161], v[186:189], 0
	v_mfma_f32_16x16x32_bf16 v[84:87], v[150:153], v[194:197], 0
	v_mfma_f32_16x16x32_bf16 v[76:79], v[158:161], v[194:197], 0
	v_mfma_f32_16x16x32_bf16 v[124:127], v[154:157], v[174:177], v[124:127]
	v_mfma_f32_16x16x32_bf16 v[120:123], v[166:169], v[174:177], v[120:123]
	v_mfma_f32_16x16x32_bf16 v[116:119], v[154:157], v[182:185], v[116:119]
	v_mfma_f32_16x16x32_bf16 v[108:111], v[166:169], v[182:185], v[108:111]
	v_mfma_f32_16x16x32_bf16 v[100:103], v[154:157], v[190:193], v[100:103]
	v_mfma_f32_16x16x32_bf16 v[92:95], v[166:169], v[190:193], v[92:95]
	v_mfma_f32_16x16x32_bf16 v[84:87], v[154:157], v[198:201], v[84:87]
	v_mfma_f32_16x16x32_bf16 v[76:79], v[166:169], v[198:201], v[76:79]
	v_mfma_f32_16x16x32_bf16 v[112:115], v[202:205], v[170:173], 0
	v_mfma_f32_16x16x32_bf16 v[104:107], v[210:213], v[170:173], 0
	v_mfma_f32_16x16x32_bf16 v[96:99], v[202:205], v[178:181], 0
	v_mfma_f32_16x16x32_bf16 v[88:91], v[210:213], v[178:181], 0
	v_mfma_f32_16x16x32_bf16 v[80:83], v[202:205], v[186:189], 0
	v_mfma_f32_16x16x32_bf16 v[72:75], v[210:213], v[186:189], 0
	v_mfma_f32_16x16x32_bf16 v[68:71], v[202:205], v[194:197], 0
	v_mfma_f32_16x16x32_bf16 v[64:67], v[210:213], v[194:197], 0
	v_mfma_f32_16x16x32_bf16 v[112:115], v[206:209], v[174:177], v[112:115]
	v_mfma_f32_16x16x32_bf16 v[104:107], v[214:217], v[174:177], v[104:107]
	v_mfma_f32_16x16x32_bf16 v[96:99], v[206:209], v[182:185], v[96:99]
	v_mfma_f32_16x16x32_bf16 v[88:91], v[214:217], v[182:185], v[88:91]
	v_mfma_f32_16x16x32_bf16 v[80:83], v[206:209], v[190:193], v[80:83]
	v_mfma_f32_16x16x32_bf16 v[72:75], v[214:217], v[190:193], v[72:75]
	v_mfma_f32_16x16x32_bf16 v[68:71], v[206:209], v[198:201], v[68:71]
	v_mfma_f32_16x16x32_bf16 v[64:67], v[214:217], v[198:201], v[64:67]
	s_barrier
	ds_read_b128 v[170:173], v163 offset:16384
	ds_read_b128 v[174:177], v163 offset:17408
	ds_read_b128 v[178:181], v163 offset:18432
	ds_read_b128 v[182:185], v163 offset:19456
	ds_read_b128 v[186:189], v163 offset:20480
	ds_read_b128 v[190:193], v163 offset:21504
	ds_read_b128 v[194:197], v163 offset:22528
	ds_read_b128 v[198:201], v163 offset:23552
	s_add_i32 s45, s66, s21
	s_mov_b32 m0, s45
	v_lshl_add_u64 v[218:219], s[54:55], 0, v[138:139]
	global_load_lds_dwordx4 v[218:219], off
	s_add_i32 m0, s45, 0x2000
	v_lshl_add_u64 v[220:221], s[54:55], 0, v[142:143]
	global_load_lds_dwordx4 v[220:221], off
	s_mov_b32 m0, s33
	v_lshl_add_u64 v[222:223], s[56:57], 0, v[136:137]
	global_load_lds_dwordx4 v[222:223], off
	s_mov_b32 m0, s35
	v_lshl_add_u64 v[224:225], s[56:57], 0, v[140:141]
	global_load_lds_dwordx4 v[224:225], off
	s_add_u32 s78, s54, 0x40000
	s_addc_u32 s79, s55, 0
	s_add_i32 s45, s67, s21
	s_mov_b32 m0, s45
	v_lshl_add_u64 v[240:241], s[78:79], 0, v[138:139]
	global_load_lds_dwordx4 v[240:241], off
	s_add_i32 m0, s45, 0x2000
	v_lshl_add_u64 v[240:241], s[78:79], 0, v[142:143]
	global_load_lds_dwordx4 v[240:241], off
	s_waitcnt vmcnt(8) lgkmcnt(0)
	s_barrier
; #define PG8_STAGE(bufoff, gbase, voff) do { _Pragma("unroll") for (int _i = 0; _i < 2; ++_i) \
;         __builtin_amdgcn_global_load_lds((const unsigned*)((const char*)(gbase) + (voff)[_i]), (LAS unsigned*)(lds + (bufoff) + ldsw + _i * 8192), 16, 0, 0); } while (0)
; #define PG8_LDA(dst, b, h) do { _Pragma("unroll") for (int m = 0; m < 4; ++m) _Pragma("unroll") for (int k = 0; k < 2; ++k) dst[m][k] = *(const LAS bf16x8*)(lds + PG8_SA(b, h) + aoff + m * 2048 + k * 1024); } while (0)
; #define PG8_LDB(dst, b, h) do { _Pragma("unroll") for (int n = 0; n < 2; ++n) _Pragma("unroll") for (int k = 0; k < 2; ++k) dst[n][k] = *(const LAS bf16x8*)(lds + PG8_SB(b, h) + boff + n * 2048 + k * 1024); } while (0)
; #define PG8_MMA(ai, bj, At, Bt) do { __builtin_amdgcn_s_setprio(1); _Pragma("unroll") for (int m = 0; m < 4; ++m) _Pragma("unroll") for (int n = 0; n < 2; ++n) _Pragma("unroll") for (int k = 0; k < 2; ++k) \
;         acc[ai][bj][m][n] = __builtin_amdgcn_mfma_f32_16x16x32_bf16(Bt[n][k], At[m][k], acc[ai][bj][m][n], 0, 0, 0); __builtin_amdgcn_s_setprio(0); } while (0)
; #define PG8_WAIT_V(n) asm volatile("s_waitcnt vmcnt(" #n ")" ::: "memory")
; #define PG8_WAIT_L(n) asm volatile("s_waitcnt lgkmcnt(" #n ")" ::: "memory")
; #define PG8_BAR __builtin_amdgcn_s_barrier()
; #define PG8_SCHED __builtin_amdgcn_sched_barrier(0)
; template <class Epi>
; __device__ __forceinline__ void gemm_phase(LAS unsigned char* lds, const Gemm g, const StaticOrder& S, const Epi& E) {
;     ...
;             PG8_BAR; PG8_WAIT_L(0); PG8_MMA(1, 0, At, B0); PG8_BAR; PG8_SCHED;
;             PG8_STAGE(PG8_SB(0, 1), b2 + hstepB, voffB);
;             PG8_WAIT_V(6); PG8_BAR; PG8_MMA(1, 1, At, B1); PG8_BAR;
;             PG8_LDB(B0, 1, 0); PG8_SCHED; PG8_LDA(At, 1, 0); PG8_STAGE(PG8_SA(0, 1), a2 + hstepA, voffA);
;             PG8_WAIT_L(8); PG8_BAR; PG8_WAIT_L(0); PG8_MMA(0, 0, At, B0); PG8_BAR; PG8_SCHED;
;             PG8_LDB(B1, 1, 1); PG8_STAGE(PG8_SB(1, 0), b3, voffB);
;             PG8_BAR; PG8_WAIT_L(0); PG8_MMA(0, 1, At, B1); PG8_BAR;
	v_mfma_f32_16x16x32_bf16 v[60:63], v[150:153], v[170:173], 0
	v_mfma_f32_16x16x32_bf16 v[56:59], v[158:161], v[170:173], 0
	v_mfma_f32_16x16x32_bf16 v[52:55], v[150:153], v[178:181], 0
	v_mfma_f32_16x16x32_bf16 v[44:47], v[158:161], v[178:181], 0
	v_mfma_f32_16x16x32_bf16 v[36:39], v[150:153], v[186:189], 0
	v_mfma_f32_16x16x32_bf16 v[28:31], v[158:161], v[186:189], 0
	v_mfma_f32_16x16x32_bf16 v[20:23], v[150:153], v[194:197], 0
	v_mfma_f32_16x16x32_bf16 v[12:15], v[158:161], v[194:197], 0
	v_mfma_f32_16x16x32_bf16 v[60:63], v[154:157], v[174:177], v[60:63]
	v_mfma_f32_16x16x32_bf16 v[56:59], v[166:169], v[174:177], v[56:59]
	v_mfma_f32_16x16x32_bf16 v[52:55], v[154:157], v[182:185], v[52:55]
	v_mfma_f32_16x16x32_bf16 v[44:47], v[166:169], v[182:185], v[44:47]
	v_mfma_f32_16x16x32_bf16 v[36:39], v[154:157], v[190:193], v[36:39]
	v_mfma_f32_16x16x32_bf16 v[28:31], v[166:169], v[190:193], v[28:31]
	v_mfma_f32_16x16x32_bf16 v[20:23], v[154:157], v[198:201], v[20:23]
	v_mfma_f32_16x16x32_bf16 v[12:15], v[166:169], v[198:201], v[12:15]
	v_mfma_f32_16x16x32_bf16 v[48:51], v[202:205], v[170:173], 0
	v_mfma_f32_16x16x32_bf16 v[40:43], v[210:213], v[170:173], 0
	v_mfma_f32_16x16x32_bf16 v[32:35], v[202:205], v[178:181], 0
	v_mfma_f32_16x16x32_bf16 v[24:27], v[210:213], v[178:181], 0
	v_mfma_f32_16x16x32_bf16 v[16:19], v[202:205], v[186:189], 0
	v_mfma_f32_16x16x32_bf16 v[8:11], v[210:213], v[186:189], 0
	v_mfma_f32_16x16x32_bf16 v[4:7], v[202:205], v[194:197], 0
	v_mfma_f32_16x16x32_bf16 v[0:3], v[210:213], v[194:197], 0
	v_mfma_f32_16x16x32_bf16 v[48:51], v[206:209], v[174:177], v[48:51]
	v_mfma_f32_16x16x32_bf16 v[40:43], v[214:217], v[174:177], v[40:43]
	v_mfma_f32_16x16x32_bf16 v[32:35], v[206:209], v[182:185], v[32:35]
	v_mfma_f32_16x16x32_bf16 v[24:27], v[214:217], v[182:185], v[24:27]
	v_mfma_f32_16x16x32_bf16 v[16:19], v[206:209], v[190:193], v[16:19]
	v_mfma_f32_16x16x32_bf16 v[8:11], v[214:217], v[190:193], v[8:11]
	v_mfma_f32_16x16x32_bf16 v[4:7], v[206:209], v[198:201], v[4:7]
	v_mfma_f32_16x16x32_bf16 v[0:3], v[214:217], v[198:201], v[0:3]
	s_barrier
	s_add_i32 s45, 0, 0x18000
	v_add_u32_e32 v165, s45, v135
	ds_read_b128 v[150:153], v165
	ds_read_b128 v[154:157], v165 offset:1024
	ds_read_b128 v[158:161], v165 offset:2048
	ds_read_b128 v[166:169], v165 offset:3072
	ds_read_b128 v[170:173], v163 offset:32768
	ds_read_b128 v[174:177], v163 offset:33792
	ds_read_b128 v[178:181], v163 offset:34816
	ds_read_b128 v[182:185], v163 offset:35840
	ds_read_b128 v[186:189], v163 offset:36864
	ds_read_b128 v[190:193], v163 offset:37888
	ds_read_b128 v[194:197], v163 offset:38912
	ds_read_b128 v[198:201], v163 offset:39936
	s_add_i32 s98, 0, 0x1c000
	v_add_u32_e32 v246, s98, v135
	ds_read_b128 v[202:205], v246
	ds_read_b128 v[206:209], v246 offset:1024
	ds_read_b128 v[210:213], v246 offset:2048
	ds_read_b128 v[214:217], v246 offset:3072
	s_add_u32 s56, s56, 0x40000
	s_addc_u32 s57, s57, 0
	s_mov_b32 m0, s58
	v_lshl_add_u64 v[244:245], s[56:57], 0, v[136:137]
	global_load_lds_dwordx4 v[244:245], off
	s_mov_b32 m0, s59
	v_lshl_add_u64 v[244:245], s[56:57], 0, v[140:141]
	global_load_lds_dwordx4 v[244:245], off
	s_waitcnt vmcnt(8) lgkmcnt(0)
	s_barrier
	v_mfma_f32_16x16x32_bf16 v[124:127], v[150:153], v[170:173], v[124:127]
	v_mfma_f32_16x16x32_bf16 v[120:123], v[158:161], v[170:173], v[120:123]
	v_mfma_f32_16x16x32_bf16 v[116:119], v[150:153], v[178:181], v[116:119]
	v_mfma_f32_16x16x32_bf16 v[108:111], v[158:161], v[178:181], v[108:111]
	v_mfma_f32_16x16x32_bf16 v[100:103], v[150:153], v[186:189], v[100:103]
	v_mfma_f32_16x16x32_bf16 v[92:95], v[158:161], v[186:189], v[92:95]
	v_mfma_f32_16x16x32_bf16 v[84:87], v[150:153], v[194:197], v[84:87]
	v_mfma_f32_16x16x32_bf16 v[76:79], v[158:161], v[194:197], v[76:79]
	v_mfma_f32_16x16x32_bf16 v[124:127], v[154:157], v[174:177], v[124:127]
	v_mfma_f32_16x16x32_bf16 v[120:123], v[166:169], v[174:177], v[120:123]
	v_mfma_f32_16x16x32_bf16 v[116:119], v[154:157], v[182:185], v[116:119]
	v_mfma_f32_16x16x32_bf16 v[108:111], v[166:169], v[182:185], v[108:111]
	v_mfma_f32_16x16x32_bf16 v[100:103], v[154:157], v[190:193], v[100:103]
	v_mfma_f32_16x16x32_bf16 v[92:95], v[166:169], v[190:193], v[92:95]
	v_mfma_f32_16x16x32_bf16 v[84:87], v[154:157], v[198:201], v[84:87]
	v_mfma_f32_16x16x32_bf16 v[76:79], v[166:169], v[198:201], v[76:79]
	v_mfma_f32_16x16x32_bf16 v[112:115], v[202:205], v[170:173], v[112:115]
	v_mfma_f32_16x16x32_bf16 v[104:107], v[210:213], v[170:173], v[104:107]
	v_mfma_f32_16x16x32_bf16 v[96:99], v[202:205], v[178:181], v[96:99]
	v_mfma_f32_16x16x32_bf16 v[88:91], v[210:213], v[178:181], v[88:91]
	v_mfma_f32_16x16x32_bf16 v[80:83], v[202:205], v[186:189], v[80:83]
	v_mfma_f32_16x16x32_bf16 v[72:75], v[210:213], v[186:189], v[72:75]
	v_mfma_f32_16x16x32_bf16 v[68:71], v[202:205], v[194:197], v[68:71]
	v_mfma_f32_16x16x32_bf16 v[64:67], v[210:213], v[194:197], v[64:67]
	v_mfma_f32_16x16x32_bf16 v[112:115], v[206:209], v[174:177], v[112:115]
	v_mfma_f32_16x16x32_bf16 v[104:107], v[214:217], v[174:177], v[104:107]
	v_mfma_f32_16x16x32_bf16 v[96:99], v[206:209], v[182:185], v[96:99]
	v_mfma_f32_16x16x32_bf16 v[88:91], v[214:217], v[182:185], v[88:91]
	v_mfma_f32_16x16x32_bf16 v[80:83], v[206:209], v[190:193], v[80:83]
	v_mfma_f32_16x16x32_bf16 v[72:75], v[214:217], v[190:193], v[72:75]
	v_mfma_f32_16x16x32_bf16 v[68:71], v[206:209], v[198:201], v[68:71]
	v_mfma_f32_16x16x32_bf16 v[64:67], v[214:217], v[198:201], v[64:67]
	s_barrier
; #define PG8_STAGE(bufoff, gbase, voff) do { _Pragma("unroll") for (int _i = 0; _i < 2; ++_i) \
;         __builtin_amdgcn_global_load_lds((const unsigned*)((const char*)(gbase) + (voff)[_i]), (LAS unsigned*)(lds + (bufoff) + ldsw + _i * 8192), 16, 0, 0); } while (0)
; #define PG8_LDA(dst, b, h) do { _Pragma("unroll") for (int m = 0; m < 4; ++m) _Pragma("unroll") for (int k = 0; k < 2; ++k) dst[m][k] = *(const LAS bf16x8*)(lds + PG8_SA(b, h) + aoff + m * 2048 + k * 1024); } while (0)
; #define PG8_MMA(ai, bj, At, Bt) do { __builtin_amdgcn_s_setprio(1); _Pragma("unroll") for (int m = 0; m < 4; ++m) _Pragma("unroll") for (int n = 0; n < 2; ++n) _Pragma("unroll") for (int k = 0; k < 2; ++k) \
;         acc[ai][bj][m][n] = __builtin_amdgcn_mfma_f32_16x16x32_bf16(Bt[n][k], At[m][k], acc[ai][bj][m][n], 0, 0, 0); __builtin_amdgcn_s_setprio(0); } while (0)
; #define PG8_WAIT_V(n) asm volatile("s_waitcnt vmcnt(" #n ")" ::: "memory")
; #define PG8_WAIT_L(n) asm volatile("s_waitcnt lgkmcnt(" #n ")" ::: "memory")
; #define PG8_BAR __builtin_amdgcn_s_barrier()
; #define PG8_SCHED __builtin_amdgcn_sched_barrier(0)
; template <class Epi>
; __device__ __forceinline__ void gemm_phase(LAS unsigned char* lds, const Gemm g, const StaticOrder& S, const Epi& E) {
;     ...
;             PG8_LDA(At, 1, 1); PG8_STAGE(PG8_SA(1, 0), a3, voffA);
;             PG8_BAR; PG8_WAIT_L(0); PG8_MMA(1, 0, At, B0); PG8_BAR; PG8_SCHED;
;             PG8_STAGE(PG8_SB(1, 1), b3 + hstepB, voffB);
;             PG8_WAIT_V(6); PG8_BAR; PG8_MMA(1, 1, At, B1); PG8_BAR;
	ds_read_b128 v[170:173], v163 offset:49152
	ds_read_b128 v[174:177], v163 offset:50176
	ds_read_b128 v[178:181], v163 offset:51200
	ds_read_b128 v[182:185], v163 offset:52224
	ds_read_b128 v[186:189], v163 offset:53248
	ds_read_b128 v[190:193], v163 offset:54272
	ds_read_b128 v[194:197], v163 offset:55296
	ds_read_b128 v[198:201], v163 offset:56320
	s_add_i32 s45, s45, s21
	s_mov_b32 m0, s45
	v_lshl_add_u64 v[218:219], v[218:219], 0, s[12:13]
	global_load_lds_dwordx4 v[218:219], off
	s_add_i32 m0, s45, 0x2000
	v_lshl_add_u64 v[218:219], v[220:221], 0, s[12:13]
	global_load_lds_dwordx4 v[218:219], off
	s_mov_b32 m0, s60
	v_lshl_add_u64 v[218:219], v[222:223], 0, s[12:13]
	global_load_lds_dwordx4 v[218:219], off
	s_mov_b32 m0, s61
	v_lshl_add_u64 v[218:219], v[224:225], 0, s[12:13]
	global_load_lds_dwordx4 v[218:219], off
	s_add_u32 s54, s54, 0x40080
	s_addc_u32 s55, s55, 0
	s_add_i32 s45, s98, s21
	s_mov_b32 m0, s45
	v_lshl_add_u64 v[240:241], s[54:55], 0, v[138:139]
	global_load_lds_dwordx4 v[240:241], off
	s_add_i32 m0, s45, 0x2000
	v_lshl_add_u64 v[240:241], s[54:55], 0, v[142:143]
	global_load_lds_dwordx4 v[240:241], off
	s_waitcnt vmcnt(8) lgkmcnt(0)
	s_barrier
	v_mfma_f32_16x16x32_bf16 v[60:63], v[150:153], v[170:173], v[60:63]
	v_mfma_f32_16x16x32_bf16 v[56:59], v[158:161], v[170:173], v[56:59]
	v_mfma_f32_16x16x32_bf16 v[52:55], v[150:153], v[178:181], v[52:55]
	v_mfma_f32_16x16x32_bf16 v[44:47], v[158:161], v[178:181], v[44:47]
	v_mfma_f32_16x16x32_bf16 v[36:39], v[150:153], v[186:189], v[36:39]
	v_mfma_f32_16x16x32_bf16 v[28:31], v[158:161], v[186:189], v[28:31]
	v_mfma_f32_16x16x32_bf16 v[20:23], v[150:153], v[194:197], v[20:23]
	v_mfma_f32_16x16x32_bf16 v[12:15], v[158:161], v[194:197], v[12:15]
	v_mfma_f32_16x16x32_bf16 v[60:63], v[154:157], v[174:177], v[60:63]
	v_mfma_f32_16x16x32_bf16 v[56:59], v[166:169], v[174:177], v[56:59]
	v_mfma_f32_16x16x32_bf16 v[52:55], v[154:157], v[182:185], v[52:55]
	v_mfma_f32_16x16x32_bf16 v[44:47], v[166:169], v[182:185], v[44:47]
	v_mfma_f32_16x16x32_bf16 v[36:39], v[154:157], v[190:193], v[36:39]
	v_mfma_f32_16x16x32_bf16 v[28:31], v[166:169], v[190:193], v[28:31]
	v_mfma_f32_16x16x32_bf16 v[20:23], v[154:157], v[198:201], v[20:23]
	v_mfma_f32_16x16x32_bf16 v[12:15], v[166:169], v[198:201], v[12:15]
	v_mfma_f32_16x16x32_bf16 v[48:51], v[202:205], v[170:173], v[48:51]
	v_mfma_f32_16x16x32_bf16 v[40:43], v[210:213], v[170:173], v[40:43]
	v_mfma_f32_16x16x32_bf16 v[32:35], v[202:205], v[178:181], v[32:35]
	v_mfma_f32_16x16x32_bf16 v[24:27], v[210:213], v[178:181], v[24:27]
	v_mfma_f32_16x16x32_bf16 v[16:19], v[202:205], v[186:189], v[16:19]
	v_mfma_f32_16x16x32_bf16 v[8:11], v[210:213], v[186:189], v[8:11]
	v_mfma_f32_16x16x32_bf16 v[4:7], v[202:205], v[194:197], v[4:7]
	v_mfma_f32_16x16x32_bf16 v[0:3], v[210:213], v[194:197], v[0:3]
	v_mfma_f32_16x16x32_bf16 v[48:51], v[206:209], v[174:177], v[48:51]
	v_mfma_f32_16x16x32_bf16 v[40:43], v[214:217], v[174:177], v[40:43]
	v_mfma_f32_16x16x32_bf16 v[32:35], v[206:209], v[182:185], v[32:35]
	v_mfma_f32_16x16x32_bf16 v[24:27], v[214:217], v[182:185], v[24:27]
	v_mfma_f32_16x16x32_bf16 v[16:19], v[206:209], v[190:193], v[16:19]
	v_mfma_f32_16x16x32_bf16 v[8:11], v[214:217], v[190:193], v[8:11]
	v_mfma_f32_16x16x32_bf16 v[4:7], v[206:209], v[198:201], v[4:7]
	v_mfma_f32_16x16x32_bf16 v[0:3], v[214:217], v[198:201], v[0:3]
	s_add_u32 s50, s50, 0x100
	s_addc_u32 s51, s51, 0
	s_add_u32 s41, s41, 0x100
	s_addc_u32 s43, s43, 0
	s_cmp_ge_i32 s77, s76
	s_mov_b32 s45, s77
	s_barrier
